# GEMM K-loops: leading half-workgroup waits for its LDS-DMA pieces after its MFMA block (one barrier later) instead of before it
# speedup vs baseline: 1.0025x; 1.0025x over previous
; #define PG8_STAGE(bufoff, gbase, voff) do { _Pragma("unroll") for (int _i = 0; _i < 2; ++_i) \
;         __builtin_amdgcn_global_load_lds((const unsigned*)((const char*)(gbase) + (voff)[_i]), (PG8_LAS unsigned*)(lds + (bufoff) + ldsw + _i * 8192), 16, 0, 0); } while (0)
; #define PG8_LDA(dst, b, h) do { _Pragma("unroll") for (int m = 0; m < 4; ++m) _Pragma("unroll") for (int k = 0; k < 2; ++k) dst[m][k] = *(const PG8_LAS bf16x8*)(lds + PG8_SA(b, h) + aoff + m * 2048 + k * 1024); } while (0)
; #define PG8_LDB(dst, b, h) do { _Pragma("unroll") for (int n = 0; n < 2; ++n) _Pragma("unroll") for (int k = 0; k < 2; ++k) dst[n][k] = *(const PG8_LAS bf16x8*)(lds + PG8_SB(b, h) + boff + n * 2048 + k * 1024); } while (0)
; #define PG8_MMA(ai, bj, At, Bt) do { __builtin_amdgcn_s_setprio(1); _Pragma("unroll") for (int m = 0; m < 4; ++m) _Pragma("unroll") for (int n = 0; n < 2; ++n) _Pragma("unroll") for (int k = 0; k < 2; ++k) \
;         acc[ai][bj][m][n] = __builtin_amdgcn_mfma_f32_16x16x32_bf16(Bt[n][k], At[m][k], acc[ai][bj][m][n], 0, 0, 0); __builtin_amdgcn_s_setprio(0); } while (0)
; #define PG8_WAIT_V(n) asm volatile("s_waitcnt vmcnt(" #n ")" ::: "memory")
; #define PG8_WAIT_L(n) asm volatile("s_waitcnt lgkmcnt(" #n ")" ::: "memory")
; template <class Epi, class Sched, bool ALIGN_EPI = false, bool SP2 = false>
; __device__ __forceinline__ void gemm_phase(PG8_LAS unsigned char* lds, const Gemm g, const Sched& S, const Epi& E) {
;     ...
;             const bool last = (t == nt - 2);
;             const char* a1 = cA + (size_t)(t + 1) * kstep;
;             const char* a2 = last ? nA : cA + (size_t)(t + 2) * kstep; const char* b2 = last ? nB : cB + (size_t)(t + 2) * kstep;
;             const char* a3 = a2 + kstep; const char* b3 = b2 + kstep;
;             if (last && has_next) S.a_ready(nxt);
;             if constexpr (SP2) {
;             PG8_LDB(B0, 0, 0); PG8_LDB(B1, 0, 1); PG8_SCHED; PG8_LDA(At, 0, 0); PG8_STAGE(PG8_SA(1, 1), a1 + hstep, voffA);
;             PG8_WAIT_V(8); PG8_WAIT_L(0); PG8_BAR; PG8_MMA(0, 0, At, B0); PG8_MMA(0, 1, At, B1); PG8_BAR; PG8_SCHED;
;             PG8_LDA(At, 0, 1); PG8_STAGE(PG8_SB(0, 0), b2, voffB); PG8_STAGE(PG8_SB(0, 1), b2 + hstep, voffB); PG8_STAGE(PG8_SA(0, 0), a2, voffA);
;             PG8_WAIT_V(8); PG8_WAIT_L(0); PG8_BAR; PG8_MMA(1, 0, At, B0); PG8_MMA(1, 1, At, B1); PG8_BAR; PG8_SCHED;
.LBB0_49:
	s_add_u32 s40, s0, 0xfffe0080
	s_addc_u32 s41, s1, -1
	s_add_i32 s65, 0, 0x10000
	s_cmp_eq_u32 s64, 4
	s_cselect_b32 s43, s19, s41
	s_cselect_b32 s42, s60, s40
	s_cselect_b32 s41, s17, s63
	s_cselect_b32 s40, s61, s62
	s_add_i32 s68, 0, 0x14000
	v_add_u32_e32 v144, s65, v248
	v_add_u32_e32 v160, s68, v248
	ds_read_b128 v[132:135], v144
	ds_read_b128 v[136:139], v144 offset:1024
	ds_read_b128 v[140:143], v144 offset:2048
	ds_read_b128 v[144:147], v144 offset:3072
	ds_read_b128 v[148:151], v160
	ds_read_b128 v[152:155], v160 offset:1024
	ds_read_b128 v[156:159], v160 offset:2048
	ds_read_b128 v[160:163], v160 offset:3072
	v_lshl_add_u64 v[210:211], s[0:1], 0, v[206:207]
	s_add_i32 m0, s51, 0xc000
	ds_read_b128 v[164:167], v250
	ds_read_b128 v[168:171], v250 offset:1024
	ds_read_b128 v[172:175], v250 offset:2048
	ds_read_b128 v[176:179], v250 offset:3072
	ds_read_b128 v[180:183], v250 offset:4096
	ds_read_b128 v[184:187], v250 offset:5120
	ds_read_b128 v[188:191], v250 offset:6144
	ds_read_b128 v[192:195], v250 offset:7168
	global_load_lds_dwordx4 v[210:211], off
	v_lshl_add_u64 v[210:211], s[0:1], 0, v[208:209]
	s_add_i32 m0, s51, 0xe000
	s_nop 0
	global_load_lds_dwordx4 v[210:211], off
	s_cmp_lg_u64 s[12:13], 0
	s_cbranch_scc1 .Lkw_49_1
	s_waitcnt vmcnt(8)
.Lkw_49_1:
	s_waitcnt lgkmcnt(0)
	v_mfma_f32_16x16x32_bf16 v[128:131], v[132:135], v[164:167], v[128:131]
	v_mfma_f32_16x16x32_bf16 v[124:127], v[140:143], v[164:167], v[124:127]
	v_mfma_f32_16x16x32_bf16 v[116:119], v[132:135], v[172:175], v[116:119]
	v_mfma_f32_16x16x32_bf16 v[108:111], v[140:143], v[172:175], v[108:111]
	s_barrier
	s_setprio 1
	v_mfma_f32_16x16x32_bf16 v[100:103], v[132:135], v[180:183], v[100:103]
	v_mfma_f32_16x16x32_bf16 v[92:95], v[140:143], v[180:183], v[92:95]
	v_mfma_f32_16x16x32_bf16 v[84:87], v[132:135], v[188:191], v[84:87]
	v_mfma_f32_16x16x32_bf16 v[76:79], v[140:143], v[188:191], v[76:79]
	v_mfma_f32_16x16x32_bf16 v[128:131], v[136:139], v[168:171], v[128:131]
	v_mfma_f32_16x16x32_bf16 v[124:127], v[144:147], v[168:171], v[124:127]
	v_mfma_f32_16x16x32_bf16 v[116:119], v[136:139], v[176:179], v[116:119]
	v_mfma_f32_16x16x32_bf16 v[108:111], v[144:147], v[176:179], v[108:111]
	v_mfma_f32_16x16x32_bf16 v[100:103], v[136:139], v[184:187], v[100:103]
	v_mfma_f32_16x16x32_bf16 v[92:95], v[144:147], v[184:187], v[92:95]
	v_mfma_f32_16x16x32_bf16 v[84:87], v[136:139], v[192:195], v[84:87]
	v_mfma_f32_16x16x32_bf16 v[76:79], v[144:147], v[192:195], v[76:79]
	s_setprio 0
	s_setprio 1
	v_mfma_f32_16x16x32_bf16 v[120:123], v[148:151], v[164:167], v[120:123]
	v_mfma_f32_16x16x32_bf16 v[112:115], v[156:159], v[164:167], v[112:115]
	v_mfma_f32_16x16x32_bf16 v[104:107], v[148:151], v[172:175], v[104:107]
	v_mfma_f32_16x16x32_bf16 v[96:99], v[156:159], v[172:175], v[96:99]
	v_mfma_f32_16x16x32_bf16 v[88:91], v[148:151], v[180:183], v[88:91]
	v_mfma_f32_16x16x32_bf16 v[80:83], v[156:159], v[180:183], v[80:83]
	v_mfma_f32_16x16x32_bf16 v[72:75], v[148:151], v[188:191], v[72:75]
	v_mfma_f32_16x16x32_bf16 v[68:71], v[156:159], v[188:191], v[68:71]
	v_mfma_f32_16x16x32_bf16 v[120:123], v[152:155], v[168:171], v[120:123]
	v_mfma_f32_16x16x32_bf16 v[112:115], v[160:163], v[168:171], v[112:115]
	v_mfma_f32_16x16x32_bf16 v[104:107], v[152:155], v[176:179], v[104:107]
	v_mfma_f32_16x16x32_bf16 v[96:99], v[160:163], v[176:179], v[96:99]
	v_mfma_f32_16x16x32_bf16 v[88:91], v[152:155], v[184:187], v[88:91]
	v_mfma_f32_16x16x32_bf16 v[80:83], v[160:163], v[184:187], v[80:83]
	v_mfma_f32_16x16x32_bf16 v[72:75], v[152:155], v[192:195], v[72:75]
	v_mfma_f32_16x16x32_bf16 v[68:71], v[160:163], v[192:195], v[68:71]
	s_setprio 0
	s_waitcnt vmcnt(8)
	s_barrier
	s_add_i32 s65, s65, s50
	v_lshl_add_u64 v[210:211], s[40:41], 0, v[196:197]
	s_mov_b32 m0, s65
	ds_read_b128 v[164:167], v250 offset:16384
	ds_read_b128 v[168:171], v250 offset:17408
	ds_read_b128 v[172:175], v250 offset:18432
	ds_read_b128 v[176:179], v250 offset:19456
	ds_read_b128 v[180:183], v250 offset:20480
	ds_read_b128 v[184:187], v250 offset:21504
	ds_read_b128 v[188:191], v250 offset:22528
	ds_read_b128 v[192:195], v250 offset:23552
	global_load_lds_dwordx4 v[210:211], off
	s_add_i32 m0, s65, 0x2000
	s_add_u32 s66, s40, 0x20000
	v_lshl_add_u64 v[212:213], s[40:41], 0, v[32:33]
	s_addc_u32 s67, s41, 0
	s_add_i32 s65, s68, s50
	global_load_lds_dwordx4 v[212:213], off
	v_lshl_add_u64 v[214:215], s[66:67], 0, v[196:197]
	s_mov_b32 m0, s65
	v_lshl_add_u64 v[216:217], s[42:43], 0, v[202:203]
	global_load_lds_dwordx4 v[214:215], off
	v_lshl_add_u64 v[214:215], s[66:67], 0, v[32:33]
	s_add_i32 m0, s65, 0x2000
	s_nop 0
	global_load_lds_dwordx4 v[214:215], off
	v_lshl_add_u64 v[214:215], s[42:43], 0, v[204:205]
	s_mov_b32 m0, s51
	s_nop 0
	global_load_lds_dwordx4 v[214:215], off
	s_mov_b32 m0, s52
	s_nop 0
	global_load_lds_dwordx4 v[216:217], off
	s_cmp_lg_u64 s[12:13], 0
	s_cbranch_scc1 .Lkw_49_2
	s_waitcnt vmcnt(8)
; #define PG8_STAGE(bufoff, gbase, voff) do { _Pragma("unroll") for (int _i = 0; _i < 2; ++_i) \
;         __builtin_amdgcn_global_load_lds((const unsigned*)((const char*)(gbase) + (voff)[_i]), (PG8_LAS unsigned*)(lds + (bufoff) + ldsw + _i * 8192), 16, 0, 0); } while (0)
; #define PG8_LDA(dst, b, h) do { _Pragma("unroll") for (int m = 0; m < 4; ++m) _Pragma("unroll") for (int k = 0; k < 2; ++k) dst[m][k] = *(const PG8_LAS bf16x8*)(lds + PG8_SA(b, h) + aoff + m * 2048 + k * 1024); } while (0)
; #define PG8_LDB(dst, b, h) do { _Pragma("unroll") for (int n = 0; n < 2; ++n) _Pragma("unroll") for (int k = 0; k < 2; ++k) dst[n][k] = *(const PG8_LAS bf16x8*)(lds + PG8_SB(b, h) + boff + n * 2048 + k * 1024); } while (0)
; #define PG8_MMA(ai, bj, At, Bt) do { __builtin_amdgcn_s_setprio(1); _Pragma("unroll") for (int m = 0; m < 4; ++m) _Pragma("unroll") for (int n = 0; n < 2; ++n) _Pragma("unroll") for (int k = 0; k < 2; ++k) \
;         acc[ai][bj][m][n] = __builtin_amdgcn_mfma_f32_16x16x32_bf16(Bt[n][k], At[m][k], acc[ai][bj][m][n], 0, 0, 0); __builtin_amdgcn_s_setprio(0); } while (0)
; #define PG8_WAIT_V(n) asm volatile("s_waitcnt vmcnt(" #n ")" ::: "memory")
; #define PG8_WAIT_L(n) asm volatile("s_waitcnt lgkmcnt(" #n ")" ::: "memory")
; #define PG8_BAR __builtin_amdgcn_s_barrier()
; #define PG8_SCHED __builtin_amdgcn_sched_barrier(0)
; template <class Epi, class Sched, bool ALIGN_EPI = false, bool SP2 = false>
; __device__ __forceinline__ void gemm_phase(PG8_LAS unsigned char* lds, const Gemm g, const Sched& S, const Epi& E) {
;     ...
;             PG8_WAIT_V(8); PG8_WAIT_L(0); PG8_BAR; PG8_MMA(1, 0, At, B0); PG8_MMA(1, 1, At, B1); PG8_BAR; PG8_SCHED;
;             PG8_LDB(B0, 1, 0); PG8_LDB(B1, 1, 1); PG8_SCHED; PG8_LDA(At, 1, 0); PG8_STAGE(PG8_SA(0, 1), a2 + hstep, voffA);
;             PG8_WAIT_V(8); PG8_WAIT_L(0); PG8_BAR; PG8_MMA(0, 0, At, B0); PG8_MMA(0, 1, At, B1); PG8_BAR; PG8_SCHED;
.Lkw_49_2:
	s_waitcnt lgkmcnt(0)
	v_mfma_f32_16x16x32_bf16 v[64:67], v[132:135], v[164:167], v[64:67]
	v_mfma_f32_16x16x32_bf16 v[60:63], v[140:143], v[164:167], v[60:63]
	v_mfma_f32_16x16x32_bf16 v[52:55], v[132:135], v[172:175], v[52:55]
	v_mfma_f32_16x16x32_bf16 v[44:47], v[140:143], v[172:175], v[44:47]
	s_barrier
	s_setprio 1
	v_mfma_f32_16x16x32_bf16 v[36:39], v[132:135], v[180:183], v[36:39]
	v_mfma_f32_16x16x32_bf16 v[24:27], v[140:143], v[180:183], v[24:27]
	v_mfma_f32_16x16x32_bf16 v[16:19], v[132:135], v[188:191], v[16:19]
	v_mfma_f32_16x16x32_bf16 v[8:11], v[140:143], v[188:191], v[8:11]
	v_mfma_f32_16x16x32_bf16 v[64:67], v[136:139], v[168:171], v[64:67]
	v_mfma_f32_16x16x32_bf16 v[60:63], v[144:147], v[168:171], v[60:63]
	v_mfma_f32_16x16x32_bf16 v[52:55], v[136:139], v[176:179], v[52:55]
	v_mfma_f32_16x16x32_bf16 v[44:47], v[144:147], v[176:179], v[44:47]
	v_mfma_f32_16x16x32_bf16 v[36:39], v[136:139], v[184:187], v[36:39]
	v_mfma_f32_16x16x32_bf16 v[24:27], v[144:147], v[184:187], v[24:27]
	v_mfma_f32_16x16x32_bf16 v[16:19], v[136:139], v[192:195], v[16:19]
	v_mfma_f32_16x16x32_bf16 v[8:11], v[144:147], v[192:195], v[8:11]
	s_setprio 0
	s_setprio 1
	v_mfma_f32_16x16x32_bf16 v[56:59], v[148:151], v[164:167], v[56:59]
	v_mfma_f32_16x16x32_bf16 v[48:51], v[156:159], v[164:167], v[48:51]
	v_mfma_f32_16x16x32_bf16 v[40:43], v[148:151], v[172:175], v[40:43]
	v_mfma_f32_16x16x32_bf16 v[28:31], v[156:159], v[172:175], v[28:31]
	v_mfma_f32_16x16x32_bf16 v[20:23], v[148:151], v[180:183], v[20:23]
	v_mfma_f32_16x16x32_bf16 v[12:15], v[156:159], v[180:183], v[12:15]
	v_mfma_f32_16x16x32_bf16 v[4:7], v[148:151], v[188:191], v[4:7]
	v_mfma_f32_16x16x32_bf16 v[0:3], v[156:159], v[188:191], v[0:3]
	v_mfma_f32_16x16x32_bf16 v[56:59], v[152:155], v[168:171], v[56:59]
	v_mfma_f32_16x16x32_bf16 v[48:51], v[160:163], v[168:171], v[48:51]
	v_mfma_f32_16x16x32_bf16 v[40:43], v[152:155], v[176:179], v[40:43]
	v_mfma_f32_16x16x32_bf16 v[28:31], v[160:163], v[176:179], v[28:31]
	v_mfma_f32_16x16x32_bf16 v[20:23], v[152:155], v[184:187], v[20:23]
	v_mfma_f32_16x16x32_bf16 v[12:15], v[160:163], v[184:187], v[12:15]
	v_mfma_f32_16x16x32_bf16 v[4:7], v[152:155], v[192:195], v[4:7]
	v_mfma_f32_16x16x32_bf16 v[0:3], v[160:163], v[192:195], v[0:3]
	s_setprio 0
	s_waitcnt vmcnt(8)
	s_barrier
	s_add_i32 s65, 0, 0x18000
	s_add_i32 s66, 0, 0x1c000
	v_add_u32_e32 v144, s65, v248
	v_add_u32_e32 v160, s66, v248
	ds_read_b128 v[132:135], v144
	ds_read_b128 v[136:139], v144 offset:1024
	ds_read_b128 v[140:143], v144 offset:2048
	ds_read_b128 v[144:147], v144 offset:3072
	ds_read_b128 v[148:151], v160
	ds_read_b128 v[152:155], v160 offset:1024
	ds_read_b128 v[156:159], v160 offset:2048
	ds_read_b128 v[160:163], v160 offset:3072
	s_add_u32 s42, s42, 0x20000
	s_addc_u32 s43, s43, 0
	s_mov_b32 m0, s53
	v_lshl_add_u64 v[218:219], s[42:43], 0, v[204:205]
	ds_read_b128 v[164:167], v250 offset:32768
	ds_read_b128 v[168:171], v250 offset:33792
	ds_read_b128 v[172:175], v250 offset:34816
	ds_read_b128 v[176:179], v250 offset:35840
	ds_read_b128 v[180:183], v250 offset:36864
	ds_read_b128 v[184:187], v250 offset:37888
	ds_read_b128 v[188:191], v250 offset:38912
	ds_read_b128 v[192:195], v250 offset:39936
	global_load_lds_dwordx4 v[218:219], off
	v_lshl_add_u64 v[218:219], s[42:43], 0, v[202:203]
	s_mov_b32 m0, s54
	s_nop 0
	global_load_lds_dwordx4 v[218:219], off
	s_cmp_lg_u64 s[12:13], 0
	s_cbranch_scc1 .Lkw_49_3
	s_waitcnt vmcnt(8)
; #define PG8_STAGE(bufoff, gbase, voff) do { _Pragma("unroll") for (int _i = 0; _i < 2; ++_i) \
;         __builtin_amdgcn_global_load_lds((const unsigned*)((const char*)(gbase) + (voff)[_i]), (PG8_LAS unsigned*)(lds + (bufoff) + ldsw + _i * 8192), 16, 0, 0); } while (0)
; #define PG8_LDA(dst, b, h) do { _Pragma("unroll") for (int m = 0; m < 4; ++m) _Pragma("unroll") for (int k = 0; k < 2; ++k) dst[m][k] = *(const PG8_LAS bf16x8*)(lds + PG8_SA(b, h) + aoff + m * 2048 + k * 1024); } while (0)
; #define PG8_MMA(ai, bj, At, Bt) do { __builtin_amdgcn_s_setprio(1); _Pragma("unroll") for (int m = 0; m < 4; ++m) _Pragma("unroll") for (int n = 0; n < 2; ++n) _Pragma("unroll") for (int k = 0; k < 2; ++k) \
;         acc[ai][bj][m][n] = __builtin_amdgcn_mfma_f32_16x16x32_bf16(Bt[n][k], At[m][k], acc[ai][bj][m][n], 0, 0, 0); __builtin_amdgcn_s_setprio(0); } while (0)
; #define PG8_WAIT_V(n) asm volatile("s_waitcnt vmcnt(" #n ")" ::: "memory")
; #define PG8_WAIT_L(n) asm volatile("s_waitcnt lgkmcnt(" #n ")" ::: "memory")
; #define PG8_BAR __builtin_amdgcn_s_barrier()
; #define PG8_SCHED __builtin_amdgcn_sched_barrier(0)
; template <class Epi, class Sched, bool ALIGN_EPI = false, bool SP2 = false>
; __device__ __forceinline__ void gemm_phase(PG8_LAS unsigned char* lds, const Gemm g, const Sched& S, const Epi& E) {
;     ...
;         for (int t = 0; t < nt; t += 2) {
;     ...
;             PG8_WAIT_V(8); PG8_WAIT_L(0); PG8_BAR; PG8_MMA(0, 0, At, B0); PG8_MMA(0, 1, At, B1); PG8_BAR; PG8_SCHED;
;             PG8_LDA(At, 1, 1); PG8_STAGE(PG8_SB(1, 0), b3, voffB); PG8_STAGE(PG8_SB(1, 1), b3 + hstep, voffB); PG8_STAGE(PG8_SA(1, 0), a3, voffA);
;             PG8_WAIT_V(8); PG8_WAIT_L(0); PG8_BAR; PG8_MMA(1, 0, At, B0); PG8_MMA(1, 1, At, B1); PG8_BAR; PG8_SCHED;
.Lkw_49_3:
	s_waitcnt lgkmcnt(0)
	v_mfma_f32_16x16x32_bf16 v[128:131], v[132:135], v[164:167], v[128:131]
	v_mfma_f32_16x16x32_bf16 v[124:127], v[140:143], v[164:167], v[124:127]
	v_mfma_f32_16x16x32_bf16 v[116:119], v[132:135], v[172:175], v[116:119]
	v_mfma_f32_16x16x32_bf16 v[108:111], v[140:143], v[172:175], v[108:111]
	s_barrier
	s_setprio 1
	v_mfma_f32_16x16x32_bf16 v[100:103], v[132:135], v[180:183], v[100:103]
	v_mfma_f32_16x16x32_bf16 v[92:95], v[140:143], v[180:183], v[92:95]
	v_mfma_f32_16x16x32_bf16 v[84:87], v[132:135], v[188:191], v[84:87]
	v_mfma_f32_16x16x32_bf16 v[76:79], v[140:143], v[188:191], v[76:79]
	v_mfma_f32_16x16x32_bf16 v[128:131], v[136:139], v[168:171], v[128:131]
	v_mfma_f32_16x16x32_bf16 v[124:127], v[144:147], v[168:171], v[124:127]
	v_mfma_f32_16x16x32_bf16 v[116:119], v[136:139], v[176:179], v[116:119]
	v_mfma_f32_16x16x32_bf16 v[108:111], v[144:147], v[176:179], v[108:111]
	v_mfma_f32_16x16x32_bf16 v[100:103], v[136:139], v[184:187], v[100:103]
	v_mfma_f32_16x16x32_bf16 v[92:95], v[144:147], v[184:187], v[92:95]
	v_mfma_f32_16x16x32_bf16 v[84:87], v[136:139], v[192:195], v[84:87]
	v_mfma_f32_16x16x32_bf16 v[76:79], v[144:147], v[192:195], v[76:79]
	s_setprio 0
	s_setprio 1
	v_mfma_f32_16x16x32_bf16 v[120:123], v[148:151], v[164:167], v[120:123]
	v_mfma_f32_16x16x32_bf16 v[112:115], v[156:159], v[164:167], v[112:115]
	v_mfma_f32_16x16x32_bf16 v[104:107], v[148:151], v[172:175], v[104:107]
	v_mfma_f32_16x16x32_bf16 v[96:99], v[156:159], v[172:175], v[96:99]
	v_mfma_f32_16x16x32_bf16 v[88:91], v[148:151], v[180:183], v[88:91]
	v_mfma_f32_16x16x32_bf16 v[80:83], v[156:159], v[180:183], v[80:83]
	v_mfma_f32_16x16x32_bf16 v[72:75], v[148:151], v[188:191], v[72:75]
	v_mfma_f32_16x16x32_bf16 v[68:71], v[156:159], v[188:191], v[68:71]
	v_mfma_f32_16x16x32_bf16 v[120:123], v[152:155], v[168:171], v[120:123]
	v_mfma_f32_16x16x32_bf16 v[112:115], v[160:163], v[168:171], v[112:115]
	v_mfma_f32_16x16x32_bf16 v[104:107], v[152:155], v[176:179], v[104:107]
	v_mfma_f32_16x16x32_bf16 v[96:99], v[160:163], v[176:179], v[96:99]
	v_mfma_f32_16x16x32_bf16 v[88:91], v[152:155], v[184:187], v[88:91]
	v_mfma_f32_16x16x32_bf16 v[80:83], v[160:163], v[184:187], v[80:83]
	v_mfma_f32_16x16x32_bf16 v[72:75], v[152:155], v[192:195], v[72:75]
	v_mfma_f32_16x16x32_bf16 v[68:71], v[160:163], v[192:195], v[68:71]
	s_setprio 0
	s_waitcnt vmcnt(8)
	s_barrier
	s_add_i32 s42, s65, s50
	v_lshl_add_u64 v[210:211], v[210:211], 0, s[36:37]
	s_mov_b32 m0, s42
	ds_read_b128 v[164:167], v250 offset:49152
	ds_read_b128 v[168:171], v250 offset:50176
	ds_read_b128 v[172:175], v250 offset:51200
	ds_read_b128 v[176:179], v250 offset:52224
	ds_read_b128 v[180:183], v250 offset:53248
	ds_read_b128 v[184:187], v250 offset:54272
	ds_read_b128 v[188:191], v250 offset:55296
	ds_read_b128 v[192:195], v250 offset:56320
	global_load_lds_dwordx4 v[210:211], off
	s_add_i32 m0, s42, 0x2000
	s_add_u32 s40, s40, 0x20080
	v_lshl_add_u64 v[210:211], v[212:213], 0, s[36:37]
	s_addc_u32 s41, s41, 0
	s_add_i32 s42, s66, s50
	global_load_lds_dwordx4 v[210:211], off
	v_lshl_add_u64 v[210:211], s[40:41], 0, v[196:197]
	s_mov_b32 m0, s42
	s_nop 0
	global_load_lds_dwordx4 v[210:211], off
	v_lshl_add_u64 v[210:211], s[40:41], 0, v[32:33]
	s_add_i32 m0, s42, 0x2000
	s_nop 0
	global_load_lds_dwordx4 v[210:211], off
	v_lshl_add_u64 v[210:211], v[214:215], 0, s[36:37]
	s_mov_b32 m0, s56
	s_nop 0
	global_load_lds_dwordx4 v[210:211], off
	v_lshl_add_u64 v[210:211], v[216:217], 0, s[36:37]
	s_mov_b32 m0, s57
	s_nop 0
	global_load_lds_dwordx4 v[210:211], off
	s_cmp_lg_u64 s[12:13], 0
	s_cbranch_scc1 .Lkw_49_4
	s_waitcnt vmcnt(8)
.Lkw_49_4:
	s_waitcnt lgkmcnt(0)
	v_mfma_f32_16x16x32_bf16 v[64:67], v[132:135], v[164:167], v[64:67]
	v_mfma_f32_16x16x32_bf16 v[60:63], v[140:143], v[164:167], v[60:63]
	v_mfma_f32_16x16x32_bf16 v[52:55], v[132:135], v[172:175], v[52:55]
	v_mfma_f32_16x16x32_bf16 v[44:47], v[140:143], v[172:175], v[44:47]
	s_barrier
	s_setprio 1
	v_mfma_f32_16x16x32_bf16 v[36:39], v[132:135], v[180:183], v[36:39]
	v_mfma_f32_16x16x32_bf16 v[24:27], v[140:143], v[180:183], v[24:27]
	v_mfma_f32_16x16x32_bf16 v[16:19], v[132:135], v[188:191], v[16:19]
	v_mfma_f32_16x16x32_bf16 v[8:11], v[140:143], v[188:191], v[8:11]
	v_mfma_f32_16x16x32_bf16 v[64:67], v[136:139], v[168:171], v[64:67]
	v_mfma_f32_16x16x32_bf16 v[60:63], v[144:147], v[168:171], v[60:63]
	v_mfma_f32_16x16x32_bf16 v[52:55], v[136:139], v[176:179], v[52:55]
	v_mfma_f32_16x16x32_bf16 v[44:47], v[144:147], v[176:179], v[44:47]
	v_mfma_f32_16x16x32_bf16 v[36:39], v[136:139], v[184:187], v[36:39]
	v_mfma_f32_16x16x32_bf16 v[24:27], v[144:147], v[184:187], v[24:27]
	v_mfma_f32_16x16x32_bf16 v[16:19], v[136:139], v[192:195], v[16:19]
	v_mfma_f32_16x16x32_bf16 v[8:11], v[144:147], v[192:195], v[8:11]
	s_setprio 0
	s_setprio 1
	v_mfma_f32_16x16x32_bf16 v[56:59], v[148:151], v[164:167], v[56:59]
	v_mfma_f32_16x16x32_bf16 v[48:51], v[156:159], v[164:167], v[48:51]
	v_mfma_f32_16x16x32_bf16 v[40:43], v[148:151], v[172:175], v[40:43]
	v_mfma_f32_16x16x32_bf16 v[28:31], v[156:159], v[172:175], v[28:31]
	v_mfma_f32_16x16x32_bf16 v[20:23], v[148:151], v[180:183], v[20:23]
	v_mfma_f32_16x16x32_bf16 v[12:15], v[156:159], v[180:183], v[12:15]
	v_mfma_f32_16x16x32_bf16 v[4:7], v[148:151], v[188:191], v[4:7]
	v_mfma_f32_16x16x32_bf16 v[0:3], v[156:159], v[188:191], v[0:3]
	v_mfma_f32_16x16x32_bf16 v[56:59], v[152:155], v[168:171], v[56:59]
	v_mfma_f32_16x16x32_bf16 v[48:51], v[160:163], v[168:171], v[48:51]
	v_mfma_f32_16x16x32_bf16 v[40:43], v[152:155], v[176:179], v[40:43]
	v_mfma_f32_16x16x32_bf16 v[28:31], v[160:163], v[176:179], v[28:31]
	v_mfma_f32_16x16x32_bf16 v[20:23], v[152:155], v[184:187], v[20:23]
	v_mfma_f32_16x16x32_bf16 v[12:15], v[160:163], v[184:187], v[12:15]
	v_mfma_f32_16x16x32_bf16 v[4:7], v[152:155], v[192:195], v[4:7]
	v_mfma_f32_16x16x32_bf16 v[0:3], v[160:163], v[192:195], v[0:3]
	s_setprio 0
	s_waitcnt vmcnt(8)
	s_barrier
	s_add_i32 s64, s64, 2
	s_add_u32 s0, s0, 0x100
	s_addc_u32 s1, s1, 0
	s_add_u32 s62, s62, 0x100
	s_addc_u32 s63, s63, 0
	s_cmp_gt_u32 s64, 5
	s_cbranch_scc0 .LBB0_49
	s_and_b64 vcc, exec, s[12:13]
	s_cbranch_vccz .LBB0_52
	s_barrier

; #define PG8_STAGE(bufoff, gbase, voff) do { _Pragma("unroll") for (int _i = 0; _i < 2; ++_i) \
;         __builtin_amdgcn_global_load_lds((const unsigned*)((const char*)(gbase) + (voff)[_i]), (PG8_LAS unsigned*)(lds + (bufoff) + ldsw + _i * 8192), 16, 0, 0); } while (0)
; #define PG8_LDA(dst, b, h) do { _Pragma("unroll") for (int m = 0; m < 4; ++m) _Pragma("unroll") for (int k = 0; k < 2; ++k) dst[m][k] = *(const PG8_LAS bf16x8*)(lds + PG8_SA(b, h) + aoff + m * 2048 + k * 1024); } while (0)
; #define PG8_LDB(dst, b, h) do { _Pragma("unroll") for (int n = 0; n < 2; ++n) _Pragma("unroll") for (int k = 0; k < 2; ++k) dst[n][k] = *(const PG8_LAS bf16x8*)(lds + PG8_SB(b, h) + boff + n * 2048 + k * 1024); } while (0)
; #define PG8_MMA(ai, bj, At, Bt) do { __builtin_amdgcn_s_setprio(1); _Pragma("unroll") for (int m = 0; m < 4; ++m) _Pragma("unroll") for (int n = 0; n < 2; ++n) _Pragma("unroll") for (int k = 0; k < 2; ++k) \
;         acc[ai][bj][m][n] = __builtin_amdgcn_mfma_f32_16x16x32_bf16(Bt[n][k], At[m][k], acc[ai][bj][m][n], 0, 0, 0); __builtin_amdgcn_s_setprio(0); } while (0)
; #define PG8_WAIT_V(n) asm volatile("s_waitcnt vmcnt(" #n ")" ::: "memory")
; #define PG8_WAIT_L(n) asm volatile("s_waitcnt lgkmcnt(" #n ")" ::: "memory")
; template <class Epi, class Sched, bool ALIGN_EPI = false, bool SP2 = false>
; __device__ __forceinline__ void gemm_phase(PG8_LAS unsigned char* lds, const Gemm g, const Sched& S, const Epi& E) {
;     ...
;             const bool last = (t == nt - 2);
;             const char* a1 = cA + (size_t)(t + 1) * kstep;
;             const char* a2 = last ? nA : cA + (size_t)(t + 2) * kstep; const char* b2 = last ? nB : cB + (size_t)(t + 2) * kstep;
;             const char* a3 = a2 + kstep; const char* b3 = b2 + kstep;
;             if (last && has_next) S.a_ready(nxt);
;             if constexpr (SP2) {
;             PG8_LDB(B0, 0, 0); PG8_LDB(B1, 0, 1); PG8_SCHED; PG8_LDA(At, 0, 0); PG8_STAGE(PG8_SA(1, 1), a1 + hstep, voffA);
;             PG8_WAIT_V(8); PG8_WAIT_L(0); PG8_BAR; PG8_MMA(0, 0, At, B0); PG8_MMA(0, 1, At, B1); PG8_BAR; PG8_SCHED;
;             PG8_LDA(At, 0, 1); PG8_STAGE(PG8_SB(0, 0), b2, voffB); PG8_STAGE(PG8_SB(0, 1), b2 + hstep, voffB); PG8_STAGE(PG8_SA(0, 0), a2, voffA);
;             PG8_WAIT_V(8); PG8_WAIT_L(0); PG8_BAR; PG8_MMA(1, 0, At, B0); PG8_MMA(1, 1, At, B1); PG8_BAR; PG8_SCHED;
.LBB0_342:
	s_add_u32 s4, s0, 0xfffc0080
	s_addc_u32 s5, s1, -1
	s_add_i32 s60, 0, 0x10000
	s_cmp_eq_u32 s59, 12
	s_cselect_b32 s43, s21, s5
	s_cselect_b32 s42, s45, s4
	s_cselect_b32 s5, s19, s58
	s_cselect_b32 s4, s46, s47
	s_add_i32 s62, 0, 0x14000
	v_add_u32_e32 v144, s60, v170
	v_add_u32_e32 v174, s62, v170
	ds_read_b128 v[132:135], v144
	ds_read_b128 v[136:139], v144 offset:1024
	ds_read_b128 v[140:143], v144 offset:2048
	ds_read_b128 v[144:147], v144 offset:3072
	ds_read_b128 v[158:161], v174
	ds_read_b128 v[162:165], v174 offset:1024
	ds_read_b128 v[166:169], v174 offset:2048
	ds_read_b128 v[174:177], v174 offset:3072
	v_lshl_add_u64 v[194:195], s[0:1], 0, v[154:155]
	s_add_i32 m0, s50, 0xc000
	ds_read_b128 v[178:181], v173
	ds_read_b128 v[182:185], v173 offset:1024
	ds_read_b128 v[186:189], v173 offset:2048
	ds_read_b128 v[190:193], v173 offset:3072
	ds_read_b128 v[202:205], v173 offset:4096
	ds_read_b128 v[206:209], v173 offset:5120
	ds_read_b128 v[210:213], v173 offset:6144
	ds_read_b128 v[214:217], v173 offset:7168
	global_load_lds_dwordx4 v[194:195], off
	v_lshl_add_u64 v[194:195], s[0:1], 0, v[156:157]
	s_add_i32 m0, s50, 0xe000
	s_nop 0
	global_load_lds_dwordx4 v[194:195], off
	s_cmp_lg_u64 s[16:17], 0
	s_cbranch_scc1 .Lkw_342_1
	s_waitcnt vmcnt(8)
.Lkw_342_1:
	s_waitcnt lgkmcnt(0)
	v_mfma_f32_16x16x32_bf16 v[128:131], v[132:135], v[178:181], v[128:131]
	v_mfma_f32_16x16x32_bf16 v[124:127], v[140:143], v[178:181], v[124:127]
	v_mfma_f32_16x16x32_bf16 v[112:115], v[132:135], v[186:189], v[112:115]
	v_mfma_f32_16x16x32_bf16 v[108:111], v[140:143], v[186:189], v[108:111]
	s_barrier
	s_setprio 1
	v_mfma_f32_16x16x32_bf16 v[96:99], v[132:135], v[202:205], v[96:99]
	v_mfma_f32_16x16x32_bf16 v[92:95], v[140:143], v[202:205], v[92:95]
	v_mfma_f32_16x16x32_bf16 v[80:83], v[132:135], v[210:213], v[80:83]
	v_mfma_f32_16x16x32_bf16 v[76:79], v[140:143], v[210:213], v[76:79]
	v_mfma_f32_16x16x32_bf16 v[128:131], v[136:139], v[182:185], v[128:131]
	v_mfma_f32_16x16x32_bf16 v[124:127], v[144:147], v[182:185], v[124:127]
	v_mfma_f32_16x16x32_bf16 v[112:115], v[136:139], v[190:193], v[112:115]
	v_mfma_f32_16x16x32_bf16 v[108:111], v[144:147], v[190:193], v[108:111]
	v_mfma_f32_16x16x32_bf16 v[96:99], v[136:139], v[206:209], v[96:99]
	v_mfma_f32_16x16x32_bf16 v[92:95], v[144:147], v[206:209], v[92:95]
	v_mfma_f32_16x16x32_bf16 v[80:83], v[136:139], v[214:217], v[80:83]
	v_mfma_f32_16x16x32_bf16 v[76:79], v[144:147], v[214:217], v[76:79]
	s_setprio 0
	s_setprio 1
	v_mfma_f32_16x16x32_bf16 v[120:123], v[158:161], v[178:181], v[120:123]
	v_mfma_f32_16x16x32_bf16 v[116:119], v[166:169], v[178:181], v[116:119]
	v_mfma_f32_16x16x32_bf16 v[104:107], v[158:161], v[186:189], v[104:107]
	v_mfma_f32_16x16x32_bf16 v[100:103], v[166:169], v[186:189], v[100:103]
	v_mfma_f32_16x16x32_bf16 v[88:91], v[158:161], v[202:205], v[88:91]
	v_mfma_f32_16x16x32_bf16 v[84:87], v[166:169], v[202:205], v[84:87]
	v_mfma_f32_16x16x32_bf16 v[72:75], v[158:161], v[210:213], v[72:75]
	v_mfma_f32_16x16x32_bf16 v[68:71], v[166:169], v[210:213], v[68:71]
	v_mfma_f32_16x16x32_bf16 v[120:123], v[162:165], v[182:185], v[120:123]
	v_mfma_f32_16x16x32_bf16 v[116:119], v[174:177], v[182:185], v[116:119]
	v_mfma_f32_16x16x32_bf16 v[104:107], v[162:165], v[190:193], v[104:107]
	v_mfma_f32_16x16x32_bf16 v[100:103], v[174:177], v[190:193], v[100:103]
	v_mfma_f32_16x16x32_bf16 v[88:91], v[162:165], v[206:209], v[88:91]
	v_mfma_f32_16x16x32_bf16 v[84:87], v[174:177], v[206:209], v[84:87]
	v_mfma_f32_16x16x32_bf16 v[72:75], v[162:165], v[214:217], v[72:75]
	v_mfma_f32_16x16x32_bf16 v[68:71], v[174:177], v[214:217], v[68:71]
	s_setprio 0
	s_waitcnt vmcnt(8)
	s_barrier
	s_add_i32 s60, s60, s49
	v_lshl_add_u64 v[194:195], s[4:5], 0, v[150:151]
	s_mov_b32 m0, s60
	ds_read_b128 v[178:181], v173 offset:16384
	ds_read_b128 v[182:185], v173 offset:17408
	ds_read_b128 v[186:189], v173 offset:18432
	ds_read_b128 v[190:193], v173 offset:19456
	ds_read_b128 v[202:205], v173 offset:20480
	ds_read_b128 v[206:209], v173 offset:21504
	ds_read_b128 v[210:213], v173 offset:22528
	ds_read_b128 v[214:217], v173 offset:23552
	global_load_lds_dwordx4 v[194:195], off
	s_add_i32 m0, s60, 0x2000
	s_add_u32 s60, s4, 0x40000
	v_lshl_add_u64 v[218:219], s[4:5], 0, v[32:33]
	s_addc_u32 s61, s5, 0
	s_add_i32 s62, s62, s49
	global_load_lds_dwordx4 v[218:219], off
	v_lshl_add_u64 v[220:221], s[60:61], 0, v[150:151]
	s_mov_b32 m0, s62
	v_lshl_add_u64 v[222:223], s[42:43], 0, v[148:149]
	global_load_lds_dwordx4 v[220:221], off
	v_lshl_add_u64 v[220:221], s[60:61], 0, v[32:33]
	s_add_i32 m0, s62, 0x2000
	s_nop 0
	global_load_lds_dwordx4 v[220:221], off
	v_lshl_add_u64 v[220:221], s[42:43], 0, v[152:153]
	s_mov_b32 m0, s50
	s_nop 0
	global_load_lds_dwordx4 v[220:221], off
	s_mov_b32 m0, s51
	s_nop 0
	global_load_lds_dwordx4 v[222:223], off
	s_cmp_lg_u64 s[16:17], 0
	s_cbranch_scc1 .Lkw_342_2
	s_waitcnt vmcnt(8)
; #define PG8_STAGE(bufoff, gbase, voff) do { _Pragma("unroll") for (int _i = 0; _i < 2; ++_i) \
;         __builtin_amdgcn_global_load_lds((const unsigned*)((const char*)(gbase) + (voff)[_i]), (PG8_LAS unsigned*)(lds + (bufoff) + ldsw + _i * 8192), 16, 0, 0); } while (0)
; #define PG8_LDA(dst, b, h) do { _Pragma("unroll") for (int m = 0; m < 4; ++m) _Pragma("unroll") for (int k = 0; k < 2; ++k) dst[m][k] = *(const PG8_LAS bf16x8*)(lds + PG8_SA(b, h) + aoff + m * 2048 + k * 1024); } while (0)
; #define PG8_LDB(dst, b, h) do { _Pragma("unroll") for (int n = 0; n < 2; ++n) _Pragma("unroll") for (int k = 0; k < 2; ++k) dst[n][k] = *(const PG8_LAS bf16x8*)(lds + PG8_SB(b, h) + boff + n * 2048 + k * 1024); } while (0)
; #define PG8_MMA(ai, bj, At, Bt) do { __builtin_amdgcn_s_setprio(1); _Pragma("unroll") for (int m = 0; m < 4; ++m) _Pragma("unroll") for (int n = 0; n < 2; ++n) _Pragma("unroll") for (int k = 0; k < 2; ++k) \
;         acc[ai][bj][m][n] = __builtin_amdgcn_mfma_f32_16x16x32_bf16(Bt[n][k], At[m][k], acc[ai][bj][m][n], 0, 0, 0); __builtin_amdgcn_s_setprio(0); } while (0)
; #define PG8_WAIT_V(n) asm volatile("s_waitcnt vmcnt(" #n ")" ::: "memory")
; #define PG8_WAIT_L(n) asm volatile("s_waitcnt lgkmcnt(" #n ")" ::: "memory")
; #define PG8_BAR __builtin_amdgcn_s_barrier()
; #define PG8_SCHED __builtin_amdgcn_sched_barrier(0)
; template <class Epi, class Sched, bool ALIGN_EPI = false, bool SP2 = false>
; __device__ __forceinline__ void gemm_phase(PG8_LAS unsigned char* lds, const Gemm g, const Sched& S, const Epi& E) {
;     ...
;             PG8_WAIT_V(8); PG8_WAIT_L(0); PG8_BAR; PG8_MMA(1, 0, At, B0); PG8_MMA(1, 1, At, B1); PG8_BAR; PG8_SCHED;
;             PG8_LDB(B0, 1, 0); PG8_LDB(B1, 1, 1); PG8_SCHED; PG8_LDA(At, 1, 0); PG8_STAGE(PG8_SA(0, 1), a2 + hstep, voffA);
;             PG8_WAIT_V(8); PG8_WAIT_L(0); PG8_BAR; PG8_MMA(0, 0, At, B0); PG8_MMA(0, 1, At, B1); PG8_BAR; PG8_SCHED;
.Lkw_342_2:
	s_waitcnt lgkmcnt(0)
	v_mfma_f32_16x16x32_bf16 v[64:67], v[132:135], v[178:181], v[64:67]
	v_mfma_f32_16x16x32_bf16 v[60:63], v[140:143], v[178:181], v[60:63]
	v_mfma_f32_16x16x32_bf16 v[48:51], v[132:135], v[186:189], v[48:51]
	v_mfma_f32_16x16x32_bf16 v[44:47], v[140:143], v[186:189], v[44:47]
	s_barrier
	s_setprio 1
	v_mfma_f32_16x16x32_bf16 v[28:31], v[132:135], v[202:205], v[28:31]
	v_mfma_f32_16x16x32_bf16 v[24:27], v[140:143], v[202:205], v[24:27]
	v_mfma_f32_16x16x32_bf16 v[12:15], v[132:135], v[210:213], v[12:15]
	v_mfma_f32_16x16x32_bf16 v[8:11], v[140:143], v[210:213], v[8:11]
	v_mfma_f32_16x16x32_bf16 v[64:67], v[136:139], v[182:185], v[64:67]
	v_mfma_f32_16x16x32_bf16 v[60:63], v[144:147], v[182:185], v[60:63]
	v_mfma_f32_16x16x32_bf16 v[48:51], v[136:139], v[190:193], v[48:51]
	v_mfma_f32_16x16x32_bf16 v[44:47], v[144:147], v[190:193], v[44:47]
	v_mfma_f32_16x16x32_bf16 v[28:31], v[136:139], v[206:209], v[28:31]
	v_mfma_f32_16x16x32_bf16 v[24:27], v[144:147], v[206:209], v[24:27]
	v_mfma_f32_16x16x32_bf16 v[12:15], v[136:139], v[214:217], v[12:15]
	v_mfma_f32_16x16x32_bf16 v[8:11], v[144:147], v[214:217], v[8:11]
	s_setprio 0
	s_setprio 1
	v_mfma_f32_16x16x32_bf16 v[56:59], v[158:161], v[178:181], v[56:59]
	v_mfma_f32_16x16x32_bf16 v[52:55], v[166:169], v[178:181], v[52:55]
	v_mfma_f32_16x16x32_bf16 v[40:43], v[158:161], v[186:189], v[40:43]
	v_mfma_f32_16x16x32_bf16 v[36:39], v[166:169], v[186:189], v[36:39]
	v_mfma_f32_16x16x32_bf16 v[20:23], v[158:161], v[202:205], v[20:23]
	v_mfma_f32_16x16x32_bf16 v[16:19], v[166:169], v[202:205], v[16:19]
	v_mfma_f32_16x16x32_bf16 v[4:7], v[158:161], v[210:213], v[4:7]
	v_mfma_f32_16x16x32_bf16 v[0:3], v[166:169], v[210:213], v[0:3]
	v_mfma_f32_16x16x32_bf16 v[56:59], v[162:165], v[182:185], v[56:59]
	v_mfma_f32_16x16x32_bf16 v[52:55], v[174:177], v[182:185], v[52:55]
	v_mfma_f32_16x16x32_bf16 v[40:43], v[162:165], v[190:193], v[40:43]
	v_mfma_f32_16x16x32_bf16 v[36:39], v[174:177], v[190:193], v[36:39]
	v_mfma_f32_16x16x32_bf16 v[20:23], v[162:165], v[206:209], v[20:23]
	v_mfma_f32_16x16x32_bf16 v[16:19], v[174:177], v[206:209], v[16:19]
	v_mfma_f32_16x16x32_bf16 v[4:7], v[162:165], v[214:217], v[4:7]
	v_mfma_f32_16x16x32_bf16 v[0:3], v[174:177], v[214:217], v[0:3]
	s_setprio 0
	s_waitcnt vmcnt(8)
	s_barrier
	s_add_i32 s60, 0, 0x18000
	s_add_i32 s61, 0, 0x1c000
	v_add_u32_e32 v144, s60, v170
	v_add_u32_e32 v174, s61, v170
	ds_read_b128 v[132:135], v144
	ds_read_b128 v[136:139], v144 offset:1024
	ds_read_b128 v[140:143], v144 offset:2048
	ds_read_b128 v[144:147], v144 offset:3072
	ds_read_b128 v[158:161], v174
	ds_read_b128 v[162:165], v174 offset:1024
	ds_read_b128 v[166:169], v174 offset:2048
	ds_read_b128 v[174:177], v174 offset:3072
	s_add_u32 s42, s42, 0x40000
	s_addc_u32 s43, s43, 0
	s_mov_b32 m0, s52
	v_lshl_add_u64 v[224:225], s[42:43], 0, v[152:153]
	ds_read_b128 v[178:181], v173 offset:32768
	ds_read_b128 v[182:185], v173 offset:33792
	ds_read_b128 v[186:189], v173 offset:34816
	ds_read_b128 v[190:193], v173 offset:35840
	ds_read_b128 v[202:205], v173 offset:36864
	ds_read_b128 v[206:209], v173 offset:37888
	ds_read_b128 v[210:213], v173 offset:38912
	ds_read_b128 v[214:217], v173 offset:39936
	global_load_lds_dwordx4 v[224:225], off
	v_lshl_add_u64 v[224:225], s[42:43], 0, v[148:149]
	s_mov_b32 m0, s53
	s_nop 0
	global_load_lds_dwordx4 v[224:225], off
	s_cmp_lg_u64 s[16:17], 0
	s_cbranch_scc1 .Lkw_342_3
	s_waitcnt vmcnt(8)
; #define PG8_STAGE(bufoff, gbase, voff) do { _Pragma("unroll") for (int _i = 0; _i < 2; ++_i) \
;         __builtin_amdgcn_global_load_lds((const unsigned*)((const char*)(gbase) + (voff)[_i]), (PG8_LAS unsigned*)(lds + (bufoff) + ldsw + _i * 8192), 16, 0, 0); } while (0)
; #define PG8_LDA(dst, b, h) do { _Pragma("unroll") for (int m = 0; m < 4; ++m) _Pragma("unroll") for (int k = 0; k < 2; ++k) dst[m][k] = *(const PG8_LAS bf16x8*)(lds + PG8_SA(b, h) + aoff + m * 2048 + k * 1024); } while (0)
; #define PG8_MMA(ai, bj, At, Bt) do { __builtin_amdgcn_s_setprio(1); _Pragma("unroll") for (int m = 0; m < 4; ++m) _Pragma("unroll") for (int n = 0; n < 2; ++n) _Pragma("unroll") for (int k = 0; k < 2; ++k) \
;         acc[ai][bj][m][n] = __builtin_amdgcn_mfma_f32_16x16x32_bf16(Bt[n][k], At[m][k], acc[ai][bj][m][n], 0, 0, 0); __builtin_amdgcn_s_setprio(0); } while (0)
; #define PG8_WAIT_V(n) asm volatile("s_waitcnt vmcnt(" #n ")" ::: "memory")
; #define PG8_WAIT_L(n) asm volatile("s_waitcnt lgkmcnt(" #n ")" ::: "memory")
; #define PG8_BAR __builtin_amdgcn_s_barrier()
; #define PG8_SCHED __builtin_amdgcn_sched_barrier(0)
; template <class Epi, class Sched, bool ALIGN_EPI = false, bool SP2 = false>
; __device__ __forceinline__ void gemm_phase(PG8_LAS unsigned char* lds, const Gemm g, const Sched& S, const Epi& E) {
;     ...
;         for (int t = 0; t < nt; t += 2) {
;     ...
;             PG8_WAIT_V(8); PG8_WAIT_L(0); PG8_BAR; PG8_MMA(0, 0, At, B0); PG8_MMA(0, 1, At, B1); PG8_BAR; PG8_SCHED;
;             PG8_LDA(At, 1, 1); PG8_STAGE(PG8_SB(1, 0), b3, voffB); PG8_STAGE(PG8_SB(1, 1), b3 + hstep, voffB); PG8_STAGE(PG8_SA(1, 0), a3, voffA);
;             PG8_WAIT_V(8); PG8_WAIT_L(0); PG8_BAR; PG8_MMA(1, 0, At, B0); PG8_MMA(1, 1, At, B1); PG8_BAR; PG8_SCHED;
.Lkw_342_3:
	s_waitcnt lgkmcnt(0)
	v_mfma_f32_16x16x32_bf16 v[128:131], v[132:135], v[178:181], v[128:131]
	v_mfma_f32_16x16x32_bf16 v[124:127], v[140:143], v[178:181], v[124:127]
	v_mfma_f32_16x16x32_bf16 v[112:115], v[132:135], v[186:189], v[112:115]
	v_mfma_f32_16x16x32_bf16 v[108:111], v[140:143], v[186:189], v[108:111]
	s_barrier
	s_setprio 1
	v_mfma_f32_16x16x32_bf16 v[96:99], v[132:135], v[202:205], v[96:99]
	v_mfma_f32_16x16x32_bf16 v[92:95], v[140:143], v[202:205], v[92:95]
	v_mfma_f32_16x16x32_bf16 v[80:83], v[132:135], v[210:213], v[80:83]
	v_mfma_f32_16x16x32_bf16 v[76:79], v[140:143], v[210:213], v[76:79]
	v_mfma_f32_16x16x32_bf16 v[128:131], v[136:139], v[182:185], v[128:131]
	v_mfma_f32_16x16x32_bf16 v[124:127], v[144:147], v[182:185], v[124:127]
	v_mfma_f32_16x16x32_bf16 v[112:115], v[136:139], v[190:193], v[112:115]
	v_mfma_f32_16x16x32_bf16 v[108:111], v[144:147], v[190:193], v[108:111]
	v_mfma_f32_16x16x32_bf16 v[96:99], v[136:139], v[206:209], v[96:99]
	v_mfma_f32_16x16x32_bf16 v[92:95], v[144:147], v[206:209], v[92:95]
	v_mfma_f32_16x16x32_bf16 v[80:83], v[136:139], v[214:217], v[80:83]
	v_mfma_f32_16x16x32_bf16 v[76:79], v[144:147], v[214:217], v[76:79]
	s_setprio 0
	s_setprio 1
	v_mfma_f32_16x16x32_bf16 v[120:123], v[158:161], v[178:181], v[120:123]
	v_mfma_f32_16x16x32_bf16 v[116:119], v[166:169], v[178:181], v[116:119]
	v_mfma_f32_16x16x32_bf16 v[104:107], v[158:161], v[186:189], v[104:107]
	v_mfma_f32_16x16x32_bf16 v[100:103], v[166:169], v[186:189], v[100:103]
	v_mfma_f32_16x16x32_bf16 v[88:91], v[158:161], v[202:205], v[88:91]
	v_mfma_f32_16x16x32_bf16 v[84:87], v[166:169], v[202:205], v[84:87]
	v_mfma_f32_16x16x32_bf16 v[72:75], v[158:161], v[210:213], v[72:75]
	v_mfma_f32_16x16x32_bf16 v[68:71], v[166:169], v[210:213], v[68:71]
	v_mfma_f32_16x16x32_bf16 v[120:123], v[162:165], v[182:185], v[120:123]
	v_mfma_f32_16x16x32_bf16 v[116:119], v[174:177], v[182:185], v[116:119]
	v_mfma_f32_16x16x32_bf16 v[104:107], v[162:165], v[190:193], v[104:107]
	v_mfma_f32_16x16x32_bf16 v[100:103], v[174:177], v[190:193], v[100:103]
	v_mfma_f32_16x16x32_bf16 v[88:91], v[162:165], v[206:209], v[88:91]
	v_mfma_f32_16x16x32_bf16 v[84:87], v[174:177], v[206:209], v[84:87]
	v_mfma_f32_16x16x32_bf16 v[72:75], v[162:165], v[214:217], v[72:75]
	v_mfma_f32_16x16x32_bf16 v[68:71], v[174:177], v[214:217], v[68:71]
	s_setprio 0
	s_waitcnt vmcnt(8)
	s_barrier
	s_add_i32 s42, s60, s49
	v_lshl_add_u64 v[194:195], v[194:195], 0, s[36:37]
	s_mov_b32 m0, s42
	ds_read_b128 v[178:181], v173 offset:49152
	ds_read_b128 v[182:185], v173 offset:50176
	ds_read_b128 v[186:189], v173 offset:51200
	ds_read_b128 v[190:193], v173 offset:52224
	ds_read_b128 v[202:205], v173 offset:53248
	ds_read_b128 v[206:209], v173 offset:54272
	ds_read_b128 v[210:213], v173 offset:55296
	ds_read_b128 v[214:217], v173 offset:56320
	global_load_lds_dwordx4 v[194:195], off
	s_add_i32 m0, s42, 0x2000
	s_add_u32 s4, s4, 0x40080
	v_lshl_add_u64 v[194:195], v[218:219], 0, s[36:37]
	s_addc_u32 s5, s5, 0
	s_add_i32 s42, s61, s49
	global_load_lds_dwordx4 v[194:195], off
	v_lshl_add_u64 v[194:195], s[4:5], 0, v[150:151]
	s_mov_b32 m0, s42
	s_nop 0
	global_load_lds_dwordx4 v[194:195], off
	v_lshl_add_u64 v[194:195], s[4:5], 0, v[32:33]
	s_add_i32 m0, s42, 0x2000
	s_nop 0
	global_load_lds_dwordx4 v[194:195], off
	v_lshl_add_u64 v[194:195], v[220:221], 0, s[36:37]
	s_mov_b32 m0, s54
	s_nop 0
	global_load_lds_dwordx4 v[194:195], off
	v_lshl_add_u64 v[194:195], v[222:223], 0, s[36:37]
	s_mov_b32 m0, s55
	s_nop 0
	global_load_lds_dwordx4 v[194:195], off
	s_cmp_lg_u64 s[16:17], 0
	s_cbranch_scc1 .Lkw_342_4
	s_waitcnt vmcnt(8)
.Lkw_342_4:
	s_waitcnt lgkmcnt(0)
	v_mfma_f32_16x16x32_bf16 v[64:67], v[132:135], v[178:181], v[64:67]
	v_mfma_f32_16x16x32_bf16 v[60:63], v[140:143], v[178:181], v[60:63]
	v_mfma_f32_16x16x32_bf16 v[48:51], v[132:135], v[186:189], v[48:51]
	v_mfma_f32_16x16x32_bf16 v[44:47], v[140:143], v[186:189], v[44:47]
	s_barrier
	s_setprio 1
	v_mfma_f32_16x16x32_bf16 v[28:31], v[132:135], v[202:205], v[28:31]
	v_mfma_f32_16x16x32_bf16 v[24:27], v[140:143], v[202:205], v[24:27]
	v_mfma_f32_16x16x32_bf16 v[12:15], v[132:135], v[210:213], v[12:15]
	v_mfma_f32_16x16x32_bf16 v[8:11], v[140:143], v[210:213], v[8:11]
	v_mfma_f32_16x16x32_bf16 v[64:67], v[136:139], v[182:185], v[64:67]
	v_mfma_f32_16x16x32_bf16 v[60:63], v[144:147], v[182:185], v[60:63]
	v_mfma_f32_16x16x32_bf16 v[48:51], v[136:139], v[190:193], v[48:51]
	v_mfma_f32_16x16x32_bf16 v[44:47], v[144:147], v[190:193], v[44:47]
	v_mfma_f32_16x16x32_bf16 v[28:31], v[136:139], v[206:209], v[28:31]
	v_mfma_f32_16x16x32_bf16 v[24:27], v[144:147], v[206:209], v[24:27]
	v_mfma_f32_16x16x32_bf16 v[12:15], v[136:139], v[214:217], v[12:15]
	v_mfma_f32_16x16x32_bf16 v[8:11], v[144:147], v[214:217], v[8:11]
	s_setprio 0
	s_setprio 1
	v_mfma_f32_16x16x32_bf16 v[56:59], v[158:161], v[178:181], v[56:59]
	v_mfma_f32_16x16x32_bf16 v[52:55], v[166:169], v[178:181], v[52:55]
	v_mfma_f32_16x16x32_bf16 v[40:43], v[158:161], v[186:189], v[40:43]
	v_mfma_f32_16x16x32_bf16 v[36:39], v[166:169], v[186:189], v[36:39]
	v_mfma_f32_16x16x32_bf16 v[20:23], v[158:161], v[202:205], v[20:23]
	v_mfma_f32_16x16x32_bf16 v[16:19], v[166:169], v[202:205], v[16:19]
	v_mfma_f32_16x16x32_bf16 v[4:7], v[158:161], v[210:213], v[4:7]
	v_mfma_f32_16x16x32_bf16 v[0:3], v[166:169], v[210:213], v[0:3]
	v_mfma_f32_16x16x32_bf16 v[56:59], v[162:165], v[182:185], v[56:59]
	v_mfma_f32_16x16x32_bf16 v[52:55], v[174:177], v[182:185], v[52:55]
	v_mfma_f32_16x16x32_bf16 v[40:43], v[162:165], v[190:193], v[40:43]
	v_mfma_f32_16x16x32_bf16 v[36:39], v[174:177], v[190:193], v[36:39]
	v_mfma_f32_16x16x32_bf16 v[20:23], v[162:165], v[206:209], v[20:23]
	v_mfma_f32_16x16x32_bf16 v[16:19], v[174:177], v[206:209], v[16:19]
	v_mfma_f32_16x16x32_bf16 v[4:7], v[162:165], v[214:217], v[4:7]
	v_mfma_f32_16x16x32_bf16 v[0:3], v[174:177], v[214:217], v[0:3]
	s_setprio 0
	s_waitcnt vmcnt(8)
	s_barrier
	s_add_i32 s59, s59, 2
	s_add_u32 s0, s0, 0x100
	s_addc_u32 s1, s1, 0
	s_add_u32 s47, s47, 0x100
	s_addc_u32 s58, s58, 0
	s_cmp_gt_u32 s59, 13
	s_cbranch_scc0 .LBB0_342
	s_and_b64 vcc, exec, s[16:17]
	s_cbranch_vccz .LBB0_345
	s_barrier

; #define PG8_STAGE(bufoff, gbase, voff) do { _Pragma("unroll") for (int _i = 0; _i < 2; ++_i) \
;         __builtin_amdgcn_global_load_lds((const unsigned*)((const char*)(gbase) + (voff)[_i]), (PG8_LAS unsigned*)(lds + (bufoff) + ldsw + _i * 8192), 16, 0, 0); } while (0)
; #define PG8_LDA(dst, b, h) do { _Pragma("unroll") for (int m = 0; m < 4; ++m) _Pragma("unroll") for (int k = 0; k < 2; ++k) dst[m][k] = *(const PG8_LAS bf16x8*)(lds + PG8_SA(b, h) + aoff + m * 2048 + k * 1024); } while (0)
; #define PG8_LDB(dst, b, h) do { _Pragma("unroll") for (int n = 0; n < 2; ++n) _Pragma("unroll") for (int k = 0; k < 2; ++k) dst[n][k] = *(const PG8_LAS bf16x8*)(lds + PG8_SB(b, h) + boff + n * 2048 + k * 1024); } while (0)
; #define PG8_MMA(ai, bj, At, Bt) do { __builtin_amdgcn_s_setprio(1); _Pragma("unroll") for (int m = 0; m < 4; ++m) _Pragma("unroll") for (int n = 0; n < 2; ++n) _Pragma("unroll") for (int k = 0; k < 2; ++k) \
;         acc[ai][bj][m][n] = __builtin_amdgcn_mfma_f32_16x16x32_bf16(Bt[n][k], At[m][k], acc[ai][bj][m][n], 0, 0, 0); __builtin_amdgcn_s_setprio(0); } while (0)
; #define PG8_WAIT_V(n) asm volatile("s_waitcnt vmcnt(" #n ")" ::: "memory")
; #define PG8_WAIT_L(n) asm volatile("s_waitcnt lgkmcnt(" #n ")" ::: "memory")
; template <class Epi, class Sched, bool ALIGN_EPI = false, bool SP2 = false>
; __device__ __forceinline__ void gemm_phase(PG8_LAS unsigned char* lds, const Gemm g, const Sched& S, const Epi& E) {
;     ...
;             const bool last = (t == nt - 2);
;             const char* a1 = cA + (size_t)(t + 1) * kstep;
;             const char* a2 = last ? nA : cA + (size_t)(t + 2) * kstep; const char* b2 = last ? nB : cB + (size_t)(t + 2) * kstep;
;             const char* a3 = a2 + kstep; const char* b3 = b2 + kstep;
;             if (last && has_next) S.a_ready(nxt);
;             if constexpr (SP2) {
;             PG8_LDB(B0, 0, 0); PG8_LDB(B1, 0, 1); PG8_SCHED; PG8_LDA(At, 0, 0); PG8_STAGE(PG8_SA(1, 1), a1 + hstep, voffA);
;             PG8_WAIT_V(8); PG8_WAIT_L(0); PG8_BAR; PG8_MMA(0, 0, At, B0); PG8_MMA(0, 1, At, B1); PG8_BAR; PG8_SCHED;
;             PG8_LDA(At, 0, 1); PG8_STAGE(PG8_SB(0, 0), b2, voffB); PG8_STAGE(PG8_SB(0, 1), b2 + hstep, voffB); PG8_STAGE(PG8_SA(0, 0), a2, voffA);
;             PG8_WAIT_V(8); PG8_WAIT_L(0); PG8_BAR; PG8_MMA(1, 0, At, B0); PG8_MMA(1, 1, At, B1); PG8_BAR; PG8_SCHED;
.LBB0_589:
	s_add_i32 s62, s40, 2
	s_add_u32 s63, s22, 0x80
	s_addc_u32 s41, s23, 0
	s_add_i32 s66, 0, 0x10000
	s_cmp_eq_u32 s56, s40
	s_cselect_b32 s41, s1, s41
	s_cselect_b32 s40, s0, s63
	s_cselect_b32 s65, s21, s61
	s_cselect_b32 s64, s20, s60
	s_add_i32 s63, 0, 0x14000
	v_add_u32_e32 v144, s66, v218
	v_add_u32_e32 v160, s63, v218
	ds_read_b128 v[132:135], v144
	ds_read_b128 v[136:139], v144 offset:1024
	ds_read_b128 v[140:143], v144 offset:2048
	ds_read_b128 v[144:147], v144 offset:3072
	ds_read_b128 v[148:151], v160
	ds_read_b128 v[152:155], v160 offset:1024
	ds_read_b128 v[156:159], v160 offset:2048
	ds_read_b128 v[160:163], v160 offset:3072
	v_lshl_add_u64 v[214:215], s[22:23], 0, v[202:203]
	s_add_i32 m0, s48, 0xc000
	ds_read_b128 v[164:167], v220
	ds_read_b128 v[168:171], v220 offset:1024
	ds_read_b128 v[172:175], v220 offset:2048
	ds_read_b128 v[176:179], v220 offset:3072
	ds_read_b128 v[180:183], v220 offset:4096
	ds_read_b128 v[184:187], v220 offset:5120
	ds_read_b128 v[206:209], v220 offset:6144
	ds_read_b128 v[210:213], v220 offset:7168
	global_load_lds_dwordx4 v[214:215], off
	v_lshl_add_u64 v[214:215], s[22:23], 0, v[204:205]
	s_add_i32 m0, s48, 0xe000
	s_nop 0
	global_load_lds_dwordx4 v[214:215], off
	s_cmp_lg_u64 s[16:17], 0
	s_cbranch_scc1 .Lkw_589_1
	s_waitcnt vmcnt(8)
.Lkw_589_1:
	s_waitcnt lgkmcnt(0)
	v_mfma_f32_16x16x32_bf16 v[128:131], v[132:135], v[164:167], v[128:131]
	v_mfma_f32_16x16x32_bf16 v[124:127], v[140:143], v[164:167], v[124:127]
	v_mfma_f32_16x16x32_bf16 v[112:115], v[132:135], v[172:175], v[112:115]
	v_mfma_f32_16x16x32_bf16 v[108:111], v[140:143], v[172:175], v[108:111]
	s_barrier
	s_setprio 1
	v_mfma_f32_16x16x32_bf16 v[96:99], v[132:135], v[180:183], v[96:99]
	v_mfma_f32_16x16x32_bf16 v[92:95], v[140:143], v[180:183], v[92:95]
	v_mfma_f32_16x16x32_bf16 v[80:83], v[132:135], v[206:209], v[80:83]
	v_mfma_f32_16x16x32_bf16 v[76:79], v[140:143], v[206:209], v[76:79]
	v_mfma_f32_16x16x32_bf16 v[128:131], v[136:139], v[168:171], v[128:131]
	v_mfma_f32_16x16x32_bf16 v[124:127], v[144:147], v[168:171], v[124:127]
	v_mfma_f32_16x16x32_bf16 v[112:115], v[136:139], v[176:179], v[112:115]
	v_mfma_f32_16x16x32_bf16 v[108:111], v[144:147], v[176:179], v[108:111]
	v_mfma_f32_16x16x32_bf16 v[96:99], v[136:139], v[184:187], v[96:99]
	v_mfma_f32_16x16x32_bf16 v[92:95], v[144:147], v[184:187], v[92:95]
	v_mfma_f32_16x16x32_bf16 v[80:83], v[136:139], v[210:213], v[80:83]
	v_mfma_f32_16x16x32_bf16 v[76:79], v[144:147], v[210:213], v[76:79]
	s_setprio 0
	s_setprio 1
	v_mfma_f32_16x16x32_bf16 v[120:123], v[148:151], v[164:167], v[120:123]
	v_mfma_f32_16x16x32_bf16 v[116:119], v[156:159], v[164:167], v[116:119]
	v_mfma_f32_16x16x32_bf16 v[104:107], v[148:151], v[172:175], v[104:107]
	v_mfma_f32_16x16x32_bf16 v[100:103], v[156:159], v[172:175], v[100:103]
	v_mfma_f32_16x16x32_bf16 v[88:91], v[148:151], v[180:183], v[88:91]
	v_mfma_f32_16x16x32_bf16 v[84:87], v[156:159], v[180:183], v[84:87]
	v_mfma_f32_16x16x32_bf16 v[72:75], v[148:151], v[206:209], v[72:75]
	v_mfma_f32_16x16x32_bf16 v[68:71], v[156:159], v[206:209], v[68:71]
	v_mfma_f32_16x16x32_bf16 v[120:123], v[152:155], v[168:171], v[120:123]
	v_mfma_f32_16x16x32_bf16 v[116:119], v[160:163], v[168:171], v[116:119]
	v_mfma_f32_16x16x32_bf16 v[104:107], v[152:155], v[176:179], v[104:107]
	v_mfma_f32_16x16x32_bf16 v[100:103], v[160:163], v[176:179], v[100:103]
	v_mfma_f32_16x16x32_bf16 v[88:91], v[152:155], v[184:187], v[88:91]
	v_mfma_f32_16x16x32_bf16 v[84:87], v[160:163], v[184:187], v[84:87]
	v_mfma_f32_16x16x32_bf16 v[72:75], v[152:155], v[210:213], v[72:75]
	v_mfma_f32_16x16x32_bf16 v[68:71], v[160:163], v[210:213], v[68:71]
	s_setprio 0
	s_waitcnt vmcnt(8)
	s_barrier
	s_add_i32 s66, s66, s47
	v_lshl_add_u64 v[214:215], s[64:65], 0, v[196:197]
	s_mov_b32 m0, s66
	ds_read_b128 v[164:167], v220 offset:16384
	ds_read_b128 v[168:171], v220 offset:17408
	ds_read_b128 v[172:175], v220 offset:18432
	ds_read_b128 v[176:179], v220 offset:19456
	ds_read_b128 v[180:183], v220 offset:20480
	ds_read_b128 v[184:187], v220 offset:21504
	ds_read_b128 v[206:209], v220 offset:22528
	ds_read_b128 v[210:213], v220 offset:23552
	global_load_lds_dwordx4 v[214:215], off
	s_add_i32 m0, s66, 0x2000
	v_lshl_add_u64 v[216:217], s[64:65], 0, v[32:33]
	s_add_u32 s64, s64, s4
	s_addc_u32 s65, s65, 0
	s_add_i32 s63, s63, s47
	global_load_lds_dwordx4 v[216:217], off
	v_lshl_add_u64 v[222:223], s[64:65], 0, v[196:197]
	s_mov_b32 m0, s63
	v_lshl_add_u64 v[224:225], s[64:65], 0, v[32:33]
	global_load_lds_dwordx4 v[222:223], off
	s_add_i32 m0, s63, 0x2000
	v_lshl_add_u64 v[226:227], s[40:41], 0, v[190:191]
	global_load_lds_dwordx4 v[224:225], off
	s_mov_b32 m0, s48
	v_lshl_add_u64 v[236:237], s[40:41], 0, v[188:189]
	global_load_lds_dwordx4 v[226:227], off
	s_mov_b32 m0, s49
	s_nop 0
	global_load_lds_dwordx4 v[236:237], off
	s_cmp_lg_u64 s[16:17], 0
	s_cbranch_scc1 .Lkw_589_2
	s_waitcnt vmcnt(8)
; #define PG8_STAGE(bufoff, gbase, voff) do { _Pragma("unroll") for (int _i = 0; _i < 2; ++_i) \
;         __builtin_amdgcn_global_load_lds((const unsigned*)((const char*)(gbase) + (voff)[_i]), (PG8_LAS unsigned*)(lds + (bufoff) + ldsw + _i * 8192), 16, 0, 0); } while (0)
; #define PG8_LDA(dst, b, h) do { _Pragma("unroll") for (int m = 0; m < 4; ++m) _Pragma("unroll") for (int k = 0; k < 2; ++k) dst[m][k] = *(const PG8_LAS bf16x8*)(lds + PG8_SA(b, h) + aoff + m * 2048 + k * 1024); } while (0)
; #define PG8_LDB(dst, b, h) do { _Pragma("unroll") for (int n = 0; n < 2; ++n) _Pragma("unroll") for (int k = 0; k < 2; ++k) dst[n][k] = *(const PG8_LAS bf16x8*)(lds + PG8_SB(b, h) + boff + n * 2048 + k * 1024); } while (0)
; #define PG8_MMA(ai, bj, At, Bt) do { __builtin_amdgcn_s_setprio(1); _Pragma("unroll") for (int m = 0; m < 4; ++m) _Pragma("unroll") for (int n = 0; n < 2; ++n) _Pragma("unroll") for (int k = 0; k < 2; ++k) \
;         acc[ai][bj][m][n] = __builtin_amdgcn_mfma_f32_16x16x32_bf16(Bt[n][k], At[m][k], acc[ai][bj][m][n], 0, 0, 0); __builtin_amdgcn_s_setprio(0); } while (0)
; #define PG8_WAIT_V(n) asm volatile("s_waitcnt vmcnt(" #n ")" ::: "memory")
; #define PG8_WAIT_L(n) asm volatile("s_waitcnt lgkmcnt(" #n ")" ::: "memory")
; #define PG8_BAR __builtin_amdgcn_s_barrier()
; #define PG8_SCHED __builtin_amdgcn_sched_barrier(0)
; template <class Epi, class Sched, bool ALIGN_EPI = false, bool SP2 = false>
; __device__ __forceinline__ void gemm_phase(PG8_LAS unsigned char* lds, const Gemm g, const Sched& S, const Epi& E) {
;     ...
;             PG8_WAIT_V(8); PG8_WAIT_L(0); PG8_BAR; PG8_MMA(1, 0, At, B0); PG8_MMA(1, 1, At, B1); PG8_BAR; PG8_SCHED;
;             PG8_LDB(B0, 1, 0); PG8_LDB(B1, 1, 1); PG8_SCHED; PG8_LDA(At, 1, 0); PG8_STAGE(PG8_SA(0, 1), a2 + hstep, voffA);
;             PG8_WAIT_V(8); PG8_WAIT_L(0); PG8_BAR; PG8_MMA(0, 0, At, B0); PG8_MMA(0, 1, At, B1); PG8_BAR; PG8_SCHED;
.Lkw_589_2:
	s_waitcnt lgkmcnt(0)
	v_mfma_f32_16x16x32_bf16 v[64:67], v[132:135], v[164:167], v[64:67]
	v_mfma_f32_16x16x32_bf16 v[60:63], v[140:143], v[164:167], v[60:63]
	v_mfma_f32_16x16x32_bf16 v[48:51], v[132:135], v[172:175], v[48:51]
	v_mfma_f32_16x16x32_bf16 v[44:47], v[140:143], v[172:175], v[44:47]
	s_barrier
	s_setprio 1
	v_mfma_f32_16x16x32_bf16 v[28:31], v[132:135], v[180:183], v[28:31]
	v_mfma_f32_16x16x32_bf16 v[24:27], v[140:143], v[180:183], v[24:27]
	v_mfma_f32_16x16x32_bf16 v[12:15], v[132:135], v[206:209], v[12:15]
	v_mfma_f32_16x16x32_bf16 v[8:11], v[140:143], v[206:209], v[8:11]
	v_mfma_f32_16x16x32_bf16 v[64:67], v[136:139], v[168:171], v[64:67]
	v_mfma_f32_16x16x32_bf16 v[60:63], v[144:147], v[168:171], v[60:63]
	v_mfma_f32_16x16x32_bf16 v[48:51], v[136:139], v[176:179], v[48:51]
	v_mfma_f32_16x16x32_bf16 v[44:47], v[144:147], v[176:179], v[44:47]
	v_mfma_f32_16x16x32_bf16 v[28:31], v[136:139], v[184:187], v[28:31]
	v_mfma_f32_16x16x32_bf16 v[24:27], v[144:147], v[184:187], v[24:27]
	v_mfma_f32_16x16x32_bf16 v[12:15], v[136:139], v[210:213], v[12:15]
	v_mfma_f32_16x16x32_bf16 v[8:11], v[144:147], v[210:213], v[8:11]
	s_setprio 0
	s_setprio 1
	v_mfma_f32_16x16x32_bf16 v[56:59], v[148:151], v[164:167], v[56:59]
	v_mfma_f32_16x16x32_bf16 v[52:55], v[156:159], v[164:167], v[52:55]
	v_mfma_f32_16x16x32_bf16 v[40:43], v[148:151], v[172:175], v[40:43]
	v_mfma_f32_16x16x32_bf16 v[36:39], v[156:159], v[172:175], v[36:39]
	v_mfma_f32_16x16x32_bf16 v[20:23], v[148:151], v[180:183], v[20:23]
	v_mfma_f32_16x16x32_bf16 v[16:19], v[156:159], v[180:183], v[16:19]
	v_mfma_f32_16x16x32_bf16 v[4:7], v[148:151], v[206:209], v[4:7]
	v_mfma_f32_16x16x32_bf16 v[0:3], v[156:159], v[206:209], v[0:3]
	v_mfma_f32_16x16x32_bf16 v[56:59], v[152:155], v[168:171], v[56:59]
	v_mfma_f32_16x16x32_bf16 v[52:55], v[160:163], v[168:171], v[52:55]
	v_mfma_f32_16x16x32_bf16 v[40:43], v[152:155], v[176:179], v[40:43]
	v_mfma_f32_16x16x32_bf16 v[36:39], v[160:163], v[176:179], v[36:39]
	v_mfma_f32_16x16x32_bf16 v[20:23], v[152:155], v[184:187], v[20:23]
	v_mfma_f32_16x16x32_bf16 v[16:19], v[160:163], v[184:187], v[16:19]
	v_mfma_f32_16x16x32_bf16 v[4:7], v[152:155], v[210:213], v[4:7]
	v_mfma_f32_16x16x32_bf16 v[0:3], v[160:163], v[210:213], v[0:3]
	s_setprio 0
	s_waitcnt vmcnt(8)
	s_barrier
	s_add_i32 s63, 0, 0x18000
	s_add_i32 s64, 0, 0x1c000
	v_add_u32_e32 v144, s63, v218
	v_add_u32_e32 v160, s64, v218
	ds_read_b128 v[132:135], v144
	ds_read_b128 v[136:139], v144 offset:1024
	ds_read_b128 v[140:143], v144 offset:2048
	ds_read_b128 v[144:147], v144 offset:3072
	ds_read_b128 v[148:151], v160
	ds_read_b128 v[152:155], v160 offset:1024
	ds_read_b128 v[156:159], v160 offset:2048
	ds_read_b128 v[160:163], v160 offset:3072
	s_add_u32 s40, s40, s4
	s_addc_u32 s41, s41, 0
	s_mov_b32 m0, s50
	v_lshl_add_u64 v[238:239], s[40:41], 0, v[190:191]
	ds_read_b128 v[164:167], v220 offset:32768
	ds_read_b128 v[168:171], v220 offset:33792
	ds_read_b128 v[172:175], v220 offset:34816
	ds_read_b128 v[176:179], v220 offset:35840
	ds_read_b128 v[180:183], v220 offset:36864
	ds_read_b128 v[184:187], v220 offset:37888
	ds_read_b128 v[206:209], v220 offset:38912
	ds_read_b128 v[210:213], v220 offset:39936
	global_load_lds_dwordx4 v[238:239], off
	v_lshl_add_u64 v[238:239], s[40:41], 0, v[188:189]
	s_mov_b32 m0, s51
	s_nop 0
	global_load_lds_dwordx4 v[238:239], off
	s_cmp_lg_u64 s[16:17], 0
	s_cbranch_scc1 .Lkw_589_3
	s_waitcnt vmcnt(8)
; #define PG8_STAGE(bufoff, gbase, voff) do { _Pragma("unroll") for (int _i = 0; _i < 2; ++_i) \
;         __builtin_amdgcn_global_load_lds((const unsigned*)((const char*)(gbase) + (voff)[_i]), (PG8_LAS unsigned*)(lds + (bufoff) + ldsw + _i * 8192), 16, 0, 0); } while (0)
; #define PG8_LDA(dst, b, h) do { _Pragma("unroll") for (int m = 0; m < 4; ++m) _Pragma("unroll") for (int k = 0; k < 2; ++k) dst[m][k] = *(const PG8_LAS bf16x8*)(lds + PG8_SA(b, h) + aoff + m * 2048 + k * 1024); } while (0)
; #define PG8_MMA(ai, bj, At, Bt) do { __builtin_amdgcn_s_setprio(1); _Pragma("unroll") for (int m = 0; m < 4; ++m) _Pragma("unroll") for (int n = 0; n < 2; ++n) _Pragma("unroll") for (int k = 0; k < 2; ++k) \
;         acc[ai][bj][m][n] = __builtin_amdgcn_mfma_f32_16x16x32_bf16(Bt[n][k], At[m][k], acc[ai][bj][m][n], 0, 0, 0); __builtin_amdgcn_s_setprio(0); } while (0)
; #define PG8_WAIT_V(n) asm volatile("s_waitcnt vmcnt(" #n ")" ::: "memory")
; #define PG8_WAIT_L(n) asm volatile("s_waitcnt lgkmcnt(" #n ")" ::: "memory")
; #define PG8_BAR __builtin_amdgcn_s_barrier()
; #define PG8_SCHED __builtin_amdgcn_sched_barrier(0)
; template <class Epi, class Sched, bool ALIGN_EPI = false, bool SP2 = false>
; __device__ __forceinline__ void gemm_phase(PG8_LAS unsigned char* lds, const Gemm g, const Sched& S, const Epi& E) {
;     ...
;         for (int t = 0; t < nt; t += 2) {
;     ...
;             PG8_WAIT_V(8); PG8_WAIT_L(0); PG8_BAR; PG8_MMA(0, 0, At, B0); PG8_MMA(0, 1, At, B1); PG8_BAR; PG8_SCHED;
;             PG8_LDA(At, 1, 1); PG8_STAGE(PG8_SB(1, 0), b3, voffB); PG8_STAGE(PG8_SB(1, 1), b3 + hstep, voffB); PG8_STAGE(PG8_SA(1, 0), a3, voffA);
;             PG8_WAIT_V(8); PG8_WAIT_L(0); PG8_BAR; PG8_MMA(1, 0, At, B0); PG8_MMA(1, 1, At, B1); PG8_BAR; PG8_SCHED;
.Lkw_589_3:
	s_waitcnt lgkmcnt(0)
	v_mfma_f32_16x16x32_bf16 v[128:131], v[132:135], v[164:167], v[128:131]
	v_mfma_f32_16x16x32_bf16 v[124:127], v[140:143], v[164:167], v[124:127]
	v_mfma_f32_16x16x32_bf16 v[112:115], v[132:135], v[172:175], v[112:115]
	v_mfma_f32_16x16x32_bf16 v[108:111], v[140:143], v[172:175], v[108:111]
	s_barrier
	s_setprio 1
	v_mfma_f32_16x16x32_bf16 v[96:99], v[132:135], v[180:183], v[96:99]
	v_mfma_f32_16x16x32_bf16 v[92:95], v[140:143], v[180:183], v[92:95]
	v_mfma_f32_16x16x32_bf16 v[80:83], v[132:135], v[206:209], v[80:83]
	v_mfma_f32_16x16x32_bf16 v[76:79], v[140:143], v[206:209], v[76:79]
	v_mfma_f32_16x16x32_bf16 v[128:131], v[136:139], v[168:171], v[128:131]
	v_mfma_f32_16x16x32_bf16 v[124:127], v[144:147], v[168:171], v[124:127]
	v_mfma_f32_16x16x32_bf16 v[112:115], v[136:139], v[176:179], v[112:115]
	v_mfma_f32_16x16x32_bf16 v[108:111], v[144:147], v[176:179], v[108:111]
	v_mfma_f32_16x16x32_bf16 v[96:99], v[136:139], v[184:187], v[96:99]
	v_mfma_f32_16x16x32_bf16 v[92:95], v[144:147], v[184:187], v[92:95]
	v_mfma_f32_16x16x32_bf16 v[80:83], v[136:139], v[210:213], v[80:83]
	v_mfma_f32_16x16x32_bf16 v[76:79], v[144:147], v[210:213], v[76:79]
	s_setprio 0
	s_setprio 1
	v_mfma_f32_16x16x32_bf16 v[120:123], v[148:151], v[164:167], v[120:123]
	v_mfma_f32_16x16x32_bf16 v[116:119], v[156:159], v[164:167], v[116:119]
	v_mfma_f32_16x16x32_bf16 v[104:107], v[148:151], v[172:175], v[104:107]
	v_mfma_f32_16x16x32_bf16 v[100:103], v[156:159], v[172:175], v[100:103]
	v_mfma_f32_16x16x32_bf16 v[88:91], v[148:151], v[180:183], v[88:91]
	v_mfma_f32_16x16x32_bf16 v[84:87], v[156:159], v[180:183], v[84:87]
	v_mfma_f32_16x16x32_bf16 v[72:75], v[148:151], v[206:209], v[72:75]
	v_mfma_f32_16x16x32_bf16 v[68:71], v[156:159], v[206:209], v[68:71]
	v_mfma_f32_16x16x32_bf16 v[120:123], v[152:155], v[168:171], v[120:123]
	v_mfma_f32_16x16x32_bf16 v[116:119], v[160:163], v[168:171], v[116:119]
	v_mfma_f32_16x16x32_bf16 v[104:107], v[152:155], v[176:179], v[104:107]
	v_mfma_f32_16x16x32_bf16 v[100:103], v[160:163], v[176:179], v[100:103]
	v_mfma_f32_16x16x32_bf16 v[88:91], v[152:155], v[184:187], v[88:91]
	v_mfma_f32_16x16x32_bf16 v[84:87], v[160:163], v[184:187], v[84:87]
	v_mfma_f32_16x16x32_bf16 v[72:75], v[152:155], v[210:213], v[72:75]
	v_mfma_f32_16x16x32_bf16 v[68:71], v[160:163], v[210:213], v[68:71]
	s_setprio 0
	s_waitcnt vmcnt(8)
	s_barrier
	s_add_i32 s40, s63, s47
	v_lshl_add_u64 v[214:215], v[214:215], 0, s[36:37]
	s_mov_b32 m0, s40
	ds_read_b128 v[164:167], v220 offset:49152
	ds_read_b128 v[168:171], v220 offset:50176
	ds_read_b128 v[172:175], v220 offset:51200
	ds_read_b128 v[176:179], v220 offset:52224
	ds_read_b128 v[180:183], v220 offset:53248
	ds_read_b128 v[184:187], v220 offset:54272
	ds_read_b128 v[206:209], v220 offset:55296
	ds_read_b128 v[210:213], v220 offset:56320
	global_load_lds_dwordx4 v[214:215], off
	v_lshl_add_u64 v[214:215], v[216:217], 0, s[36:37]
	s_add_i32 m0, s40, 0x2000
	s_add_i32 s40, s64, s47
	global_load_lds_dwordx4 v[214:215], off
	v_lshl_add_u64 v[214:215], v[222:223], 0, s[36:37]
	s_mov_b32 m0, s40
	s_nop 0
	global_load_lds_dwordx4 v[214:215], off
	v_lshl_add_u64 v[214:215], v[224:225], 0, s[36:37]
	s_add_i32 m0, s40, 0x2000
	s_nop 0
	global_load_lds_dwordx4 v[214:215], off
	v_lshl_add_u64 v[214:215], v[226:227], 0, s[36:37]
	s_mov_b32 m0, s52
	s_nop 0
	global_load_lds_dwordx4 v[214:215], off
	v_lshl_add_u64 v[214:215], v[236:237], 0, s[36:37]
	s_mov_b32 m0, s53
	s_nop 0
	global_load_lds_dwordx4 v[214:215], off
	s_cmp_lg_u64 s[16:17], 0
	s_cbranch_scc1 .Lkw_589_4
	s_waitcnt vmcnt(8)
.Lkw_589_4:
	s_waitcnt lgkmcnt(0)
	v_mfma_f32_16x16x32_bf16 v[64:67], v[132:135], v[164:167], v[64:67]
	v_mfma_f32_16x16x32_bf16 v[60:63], v[140:143], v[164:167], v[60:63]
	v_mfma_f32_16x16x32_bf16 v[48:51], v[132:135], v[172:175], v[48:51]
	v_mfma_f32_16x16x32_bf16 v[44:47], v[140:143], v[172:175], v[44:47]
	s_barrier
	s_setprio 1
	v_mfma_f32_16x16x32_bf16 v[28:31], v[132:135], v[180:183], v[28:31]
	v_mfma_f32_16x16x32_bf16 v[24:27], v[140:143], v[180:183], v[24:27]
	v_mfma_f32_16x16x32_bf16 v[12:15], v[132:135], v[206:209], v[12:15]
	v_mfma_f32_16x16x32_bf16 v[8:11], v[140:143], v[206:209], v[8:11]
	v_mfma_f32_16x16x32_bf16 v[64:67], v[136:139], v[168:171], v[64:67]
	v_mfma_f32_16x16x32_bf16 v[60:63], v[144:147], v[168:171], v[60:63]
	v_mfma_f32_16x16x32_bf16 v[48:51], v[136:139], v[176:179], v[48:51]
	v_mfma_f32_16x16x32_bf16 v[44:47], v[144:147], v[176:179], v[44:47]
	v_mfma_f32_16x16x32_bf16 v[28:31], v[136:139], v[184:187], v[28:31]
	v_mfma_f32_16x16x32_bf16 v[24:27], v[144:147], v[184:187], v[24:27]
	v_mfma_f32_16x16x32_bf16 v[12:15], v[136:139], v[210:213], v[12:15]
	v_mfma_f32_16x16x32_bf16 v[8:11], v[144:147], v[210:213], v[8:11]
	s_setprio 0
	s_setprio 1
	v_mfma_f32_16x16x32_bf16 v[56:59], v[148:151], v[164:167], v[56:59]
	v_mfma_f32_16x16x32_bf16 v[52:55], v[156:159], v[164:167], v[52:55]
	v_mfma_f32_16x16x32_bf16 v[40:43], v[148:151], v[172:175], v[40:43]
	v_mfma_f32_16x16x32_bf16 v[36:39], v[156:159], v[172:175], v[36:39]
	v_mfma_f32_16x16x32_bf16 v[20:23], v[148:151], v[180:183], v[20:23]
	v_mfma_f32_16x16x32_bf16 v[16:19], v[156:159], v[180:183], v[16:19]
	v_mfma_f32_16x16x32_bf16 v[4:7], v[148:151], v[206:209], v[4:7]
	v_mfma_f32_16x16x32_bf16 v[0:3], v[156:159], v[206:209], v[0:3]
	v_mfma_f32_16x16x32_bf16 v[56:59], v[152:155], v[168:171], v[56:59]
	v_mfma_f32_16x16x32_bf16 v[52:55], v[160:163], v[168:171], v[52:55]
	v_mfma_f32_16x16x32_bf16 v[40:43], v[152:155], v[176:179], v[40:43]
	v_mfma_f32_16x16x32_bf16 v[36:39], v[160:163], v[176:179], v[36:39]
	v_mfma_f32_16x16x32_bf16 v[20:23], v[152:155], v[184:187], v[20:23]
	v_mfma_f32_16x16x32_bf16 v[16:19], v[160:163], v[184:187], v[16:19]
	v_mfma_f32_16x16x32_bf16 v[4:7], v[152:155], v[210:213], v[4:7]
	v_mfma_f32_16x16x32_bf16 v[0:3], v[160:163], v[210:213], v[0:3]
	s_setprio 0
	s_waitcnt vmcnt(8)
	s_barrier
	s_add_u32 s22, s22, 0x100
	s_addc_u32 s23, s23, 0
	s_add_u32 s60, s60, 0x100
	s_addc_u32 s61, s61, 0
	s_cmp_ge_u32 s62, s55
	s_mov_b32 s40, s62
	s_cbranch_scc0 .LBB0_589
	s_and_b64 vcc, exec, s[16:17]
	s_cbranch_vccz .LBB0_592
	s_barrier

; #define PG8_STAGE(bufoff, gbase, voff) do { _Pragma("unroll") for (int _i = 0; _i < 2; ++_i) \
;         __builtin_amdgcn_global_load_lds((const unsigned*)((const char*)(gbase) + (voff)[_i]), (PG8_LAS unsigned*)(lds + (bufoff) + ldsw + _i * 8192), 16, 0, 0); } while (0)
; #define PG8_LDA(dst, b, h) do { _Pragma("unroll") for (int m = 0; m < 4; ++m) _Pragma("unroll") for (int k = 0; k < 2; ++k) dst[m][k] = *(const PG8_LAS bf16x8*)(lds + PG8_SA(b, h) + aoff + m * 2048 + k * 1024); } while (0)
; #define PG8_LDB(dst, b, h) do { _Pragma("unroll") for (int n = 0; n < 2; ++n) _Pragma("unroll") for (int k = 0; k < 2; ++k) dst[n][k] = *(const PG8_LAS bf16x8*)(lds + PG8_SB(b, h) + boff + n * 2048 + k * 1024); } while (0)
; #define PG8_MMA(ai, bj, At, Bt) do { __builtin_amdgcn_s_setprio(1); _Pragma("unroll") for (int m = 0; m < 4; ++m) _Pragma("unroll") for (int n = 0; n < 2; ++n) _Pragma("unroll") for (int k = 0; k < 2; ++k) \
;         acc[ai][bj][m][n] = __builtin_amdgcn_mfma_f32_16x16x32_bf16(Bt[n][k], At[m][k], acc[ai][bj][m][n], 0, 0, 0); __builtin_amdgcn_s_setprio(0); } while (0)
; #define PG8_WAIT_V(n) asm volatile("s_waitcnt vmcnt(" #n ")" ::: "memory")
; #define PG8_WAIT_L(n) asm volatile("s_waitcnt lgkmcnt(" #n ")" ::: "memory")
; template <class Epi, class Sched, bool ALIGN_EPI = false, bool SP2 = false>
; __device__ __forceinline__ void gemm_phase(PG8_LAS unsigned char* lds, const Gemm g, const Sched& S, const Epi& E) {
;     ...
;             const bool last = (t == nt - 2);
;             const char* a1 = cA + (size_t)(t + 1) * kstep;
;             const char* a2 = last ? nA : cA + (size_t)(t + 2) * kstep; const char* b2 = last ? nB : cB + (size_t)(t + 2) * kstep;
;             const char* a3 = a2 + kstep; const char* b3 = b2 + kstep;
;             if (last && has_next) S.a_ready(nxt);
;             if constexpr (SP2) {
;             PG8_LDB(B0, 0, 0); PG8_LDB(B1, 0, 1); PG8_SCHED; PG8_LDA(At, 0, 0); PG8_STAGE(PG8_SA(1, 1), a1 + hstep, voffA);
;             PG8_WAIT_V(8); PG8_WAIT_L(0); PG8_BAR; PG8_MMA(0, 0, At, B0); PG8_MMA(0, 1, At, B1); PG8_BAR; PG8_SCHED;
;             PG8_LDA(At, 0, 1); PG8_STAGE(PG8_SB(0, 0), b2, voffB); PG8_STAGE(PG8_SB(0, 1), b2 + hstep, voffB); PG8_STAGE(PG8_SA(0, 0), a2, voffA);
;             PG8_WAIT_V(8); PG8_WAIT_L(0); PG8_BAR; PG8_MMA(1, 0, At, B0); PG8_MMA(1, 1, At, B1); PG8_BAR; PG8_SCHED;
.LBB0_623:
	s_add_u32 s22, s0, 0xfffc0080
	s_addc_u32 s23, s1, -1
	s_add_i32 s58, 0, 0x10000
	s_cmp_eq_u32 s57, 12
	s_cselect_b32 s41, s17, s23
	s_cselect_b32 s40, s53, s22
	v_add_u32_e32 v144, s58, v147
	s_cselect_b32 s23, s15, s56
	s_cselect_b32 s22, s54, s55
	s_add_i32 s60, 0, 0x14000
	ds_read_b128 v[140:143], v144
	ds_read_b128 v[150:153], v144 offset:1024
	ds_read_b128 v[154:157], v144 offset:2048
	ds_read_b128 v[158:161], v144 offset:3072
	v_add_u32_e32 v144, s60, v147
	ds_read_b128 v[162:165], v144
	ds_read_b128 v[166:169], v144 offset:1024
	ds_read_b128 v[170:173], v144 offset:2048
	ds_read_b128 v[174:177], v144 offset:3072
	v_lshl_add_u64 v[144:145], s[0:1], 0, v[136:137]
	s_add_i32 m0, s44, 0xc000
	ds_read_b128 v[178:181], v149
	ds_read_b128 v[182:185], v149 offset:1024
	ds_read_b128 v[186:189], v149 offset:2048
	ds_read_b128 v[190:193], v149 offset:3072
	ds_read_b128 v[202:205], v149 offset:4096
	ds_read_b128 v[206:209], v149 offset:5120
	ds_read_b128 v[210:213], v149 offset:6144
	ds_read_b128 v[214:217], v149 offset:7168
	global_load_lds_dwordx4 v[144:145], off
	v_lshl_add_u64 v[144:145], s[0:1], 0, v[138:139]
	s_add_i32 m0, s44, 0xe000
	s_nop 0
	global_load_lds_dwordx4 v[144:145], off
	s_cmp_lg_u64 s[12:13], 0
	s_cbranch_scc1 .Lkw_623_1
	s_waitcnt vmcnt(8)
.Lkw_623_1:
	s_waitcnt lgkmcnt(0)
	v_mfma_f32_16x16x32_bf16 v[128:131], v[140:143], v[178:181], v[128:131]
	v_mfma_f32_16x16x32_bf16 v[124:127], v[154:157], v[178:181], v[124:127]
	v_mfma_f32_16x16x32_bf16 v[112:115], v[140:143], v[186:189], v[112:115]
	v_mfma_f32_16x16x32_bf16 v[108:111], v[154:157], v[186:189], v[108:111]
	s_barrier
	s_setprio 1
	v_mfma_f32_16x16x32_bf16 v[96:99], v[140:143], v[202:205], v[96:99]
	v_mfma_f32_16x16x32_bf16 v[92:95], v[154:157], v[202:205], v[92:95]
	v_mfma_f32_16x16x32_bf16 v[80:83], v[140:143], v[210:213], v[80:83]
	v_mfma_f32_16x16x32_bf16 v[76:79], v[154:157], v[210:213], v[76:79]
	v_mfma_f32_16x16x32_bf16 v[128:131], v[150:153], v[182:185], v[128:131]
	v_mfma_f32_16x16x32_bf16 v[124:127], v[158:161], v[182:185], v[124:127]
	v_mfma_f32_16x16x32_bf16 v[112:115], v[150:153], v[190:193], v[112:115]
	v_mfma_f32_16x16x32_bf16 v[108:111], v[158:161], v[190:193], v[108:111]
	v_mfma_f32_16x16x32_bf16 v[96:99], v[150:153], v[206:209], v[96:99]
	v_mfma_f32_16x16x32_bf16 v[92:95], v[158:161], v[206:209], v[92:95]
	v_mfma_f32_16x16x32_bf16 v[80:83], v[150:153], v[214:217], v[80:83]
	v_mfma_f32_16x16x32_bf16 v[76:79], v[158:161], v[214:217], v[76:79]
	s_setprio 0
	s_setprio 1
	v_mfma_f32_16x16x32_bf16 v[120:123], v[162:165], v[178:181], v[120:123]
	v_mfma_f32_16x16x32_bf16 v[116:119], v[170:173], v[178:181], v[116:119]
	v_mfma_f32_16x16x32_bf16 v[104:107], v[162:165], v[186:189], v[104:107]
	v_mfma_f32_16x16x32_bf16 v[100:103], v[170:173], v[186:189], v[100:103]
	v_mfma_f32_16x16x32_bf16 v[88:91], v[162:165], v[202:205], v[88:91]
	v_mfma_f32_16x16x32_bf16 v[84:87], v[170:173], v[202:205], v[84:87]
	v_mfma_f32_16x16x32_bf16 v[72:75], v[162:165], v[210:213], v[72:75]
	v_mfma_f32_16x16x32_bf16 v[68:71], v[170:173], v[210:213], v[68:71]
	v_mfma_f32_16x16x32_bf16 v[120:123], v[166:169], v[182:185], v[120:123]
	v_mfma_f32_16x16x32_bf16 v[116:119], v[174:177], v[182:185], v[116:119]
	v_mfma_f32_16x16x32_bf16 v[104:107], v[166:169], v[190:193], v[104:107]
	v_mfma_f32_16x16x32_bf16 v[100:103], v[174:177], v[190:193], v[100:103]
	v_mfma_f32_16x16x32_bf16 v[88:91], v[166:169], v[206:209], v[88:91]
	v_mfma_f32_16x16x32_bf16 v[84:87], v[174:177], v[206:209], v[84:87]
	v_mfma_f32_16x16x32_bf16 v[72:75], v[166:169], v[214:217], v[72:75]
	v_mfma_f32_16x16x32_bf16 v[68:71], v[174:177], v[214:217], v[68:71]
	s_setprio 0
	s_waitcnt vmcnt(8)
	s_barrier
	s_add_i32 s58, s58, s43
	v_lshl_add_u64 v[144:145], s[22:23], 0, v[196:197]
	s_mov_b32 m0, s58
	ds_read_b128 v[178:181], v149 offset:16384
	ds_read_b128 v[182:185], v149 offset:17408
	ds_read_b128 v[186:189], v149 offset:18432
	ds_read_b128 v[190:193], v149 offset:19456
	ds_read_b128 v[202:205], v149 offset:20480
	ds_read_b128 v[206:209], v149 offset:21504
	ds_read_b128 v[210:213], v149 offset:22528
	ds_read_b128 v[214:217], v149 offset:23552
	global_load_lds_dwordx4 v[144:145], off
	s_add_i32 m0, s58, 0x2000
	s_add_u32 s58, s22, 0x40000
	v_lshl_add_u64 v[194:195], s[22:23], 0, v[32:33]
	s_addc_u32 s59, s23, 0
	s_add_i32 s60, s60, s43
	global_load_lds_dwordx4 v[194:195], off
	v_lshl_add_u64 v[218:219], s[58:59], 0, v[196:197]
	s_mov_b32 m0, s60
	v_lshl_add_u64 v[220:221], s[40:41], 0, v[132:133]
	global_load_lds_dwordx4 v[218:219], off
	v_lshl_add_u64 v[218:219], s[58:59], 0, v[32:33]
	s_add_i32 m0, s60, 0x2000
	s_nop 0
	global_load_lds_dwordx4 v[218:219], off
	v_lshl_add_u64 v[218:219], s[40:41], 0, v[134:135]
	s_mov_b32 m0, s44
	s_nop 0
	global_load_lds_dwordx4 v[218:219], off
	s_mov_b32 m0, s45
	s_nop 0
	global_load_lds_dwordx4 v[220:221], off
	s_cmp_lg_u64 s[12:13], 0
	s_cbranch_scc1 .Lkw_623_2
	s_waitcnt vmcnt(8)
; #define PG8_STAGE(bufoff, gbase, voff) do { _Pragma("unroll") for (int _i = 0; _i < 2; ++_i) \
;         __builtin_amdgcn_global_load_lds((const unsigned*)((const char*)(gbase) + (voff)[_i]), (PG8_LAS unsigned*)(lds + (bufoff) + ldsw + _i * 8192), 16, 0, 0); } while (0)
; #define PG8_LDA(dst, b, h) do { _Pragma("unroll") for (int m = 0; m < 4; ++m) _Pragma("unroll") for (int k = 0; k < 2; ++k) dst[m][k] = *(const PG8_LAS bf16x8*)(lds + PG8_SA(b, h) + aoff + m * 2048 + k * 1024); } while (0)
; #define PG8_LDB(dst, b, h) do { _Pragma("unroll") for (int n = 0; n < 2; ++n) _Pragma("unroll") for (int k = 0; k < 2; ++k) dst[n][k] = *(const PG8_LAS bf16x8*)(lds + PG8_SB(b, h) + boff + n * 2048 + k * 1024); } while (0)
; #define PG8_MMA(ai, bj, At, Bt) do { __builtin_amdgcn_s_setprio(1); _Pragma("unroll") for (int m = 0; m < 4; ++m) _Pragma("unroll") for (int n = 0; n < 2; ++n) _Pragma("unroll") for (int k = 0; k < 2; ++k) \
;         acc[ai][bj][m][n] = __builtin_amdgcn_mfma_f32_16x16x32_bf16(Bt[n][k], At[m][k], acc[ai][bj][m][n], 0, 0, 0); __builtin_amdgcn_s_setprio(0); } while (0)
; #define PG8_WAIT_V(n) asm volatile("s_waitcnt vmcnt(" #n ")" ::: "memory")
; #define PG8_WAIT_L(n) asm volatile("s_waitcnt lgkmcnt(" #n ")" ::: "memory")
; #define PG8_BAR __builtin_amdgcn_s_barrier()
; #define PG8_SCHED __builtin_amdgcn_sched_barrier(0)
; template <class Epi, class Sched, bool ALIGN_EPI = false, bool SP2 = false>
; __device__ __forceinline__ void gemm_phase(PG8_LAS unsigned char* lds, const Gemm g, const Sched& S, const Epi& E) {
;     ...
;             PG8_WAIT_V(8); PG8_WAIT_L(0); PG8_BAR; PG8_MMA(1, 0, At, B0); PG8_MMA(1, 1, At, B1); PG8_BAR; PG8_SCHED;
;             PG8_LDB(B0, 1, 0); PG8_LDB(B1, 1, 1); PG8_SCHED; PG8_LDA(At, 1, 0); PG8_STAGE(PG8_SA(0, 1), a2 + hstep, voffA);
;             PG8_WAIT_V(8); PG8_WAIT_L(0); PG8_BAR; PG8_MMA(0, 0, At, B0); PG8_MMA(0, 1, At, B1); PG8_BAR; PG8_SCHED;
.Lkw_623_2:
	s_waitcnt lgkmcnt(0)
	v_mfma_f32_16x16x32_bf16 v[64:67], v[140:143], v[178:181], v[64:67]
	v_mfma_f32_16x16x32_bf16 v[60:63], v[154:157], v[178:181], v[60:63]
	v_mfma_f32_16x16x32_bf16 v[48:51], v[140:143], v[186:189], v[48:51]
	v_mfma_f32_16x16x32_bf16 v[44:47], v[154:157], v[186:189], v[44:47]
	s_barrier
	s_setprio 1
	v_mfma_f32_16x16x32_bf16 v[28:31], v[140:143], v[202:205], v[28:31]
	v_mfma_f32_16x16x32_bf16 v[24:27], v[154:157], v[202:205], v[24:27]
	v_mfma_f32_16x16x32_bf16 v[12:15], v[140:143], v[210:213], v[12:15]
	v_mfma_f32_16x16x32_bf16 v[8:11], v[154:157], v[210:213], v[8:11]
	v_mfma_f32_16x16x32_bf16 v[64:67], v[150:153], v[182:185], v[64:67]
	v_mfma_f32_16x16x32_bf16 v[60:63], v[158:161], v[182:185], v[60:63]
	v_mfma_f32_16x16x32_bf16 v[48:51], v[150:153], v[190:193], v[48:51]
	v_mfma_f32_16x16x32_bf16 v[44:47], v[158:161], v[190:193], v[44:47]
	v_mfma_f32_16x16x32_bf16 v[28:31], v[150:153], v[206:209], v[28:31]
	v_mfma_f32_16x16x32_bf16 v[24:27], v[158:161], v[206:209], v[24:27]
	v_mfma_f32_16x16x32_bf16 v[12:15], v[150:153], v[214:217], v[12:15]
	v_mfma_f32_16x16x32_bf16 v[8:11], v[158:161], v[214:217], v[8:11]
	s_setprio 0
	s_setprio 1
	v_mfma_f32_16x16x32_bf16 v[56:59], v[162:165], v[178:181], v[56:59]
	v_mfma_f32_16x16x32_bf16 v[52:55], v[170:173], v[178:181], v[52:55]
	v_mfma_f32_16x16x32_bf16 v[40:43], v[162:165], v[186:189], v[40:43]
	v_mfma_f32_16x16x32_bf16 v[36:39], v[170:173], v[186:189], v[36:39]
	v_mfma_f32_16x16x32_bf16 v[20:23], v[162:165], v[202:205], v[20:23]
	v_mfma_f32_16x16x32_bf16 v[16:19], v[170:173], v[202:205], v[16:19]
	v_mfma_f32_16x16x32_bf16 v[4:7], v[162:165], v[210:213], v[4:7]
	v_mfma_f32_16x16x32_bf16 v[0:3], v[170:173], v[210:213], v[0:3]
	v_mfma_f32_16x16x32_bf16 v[56:59], v[166:169], v[182:185], v[56:59]
	v_mfma_f32_16x16x32_bf16 v[52:55], v[174:177], v[182:185], v[52:55]
	v_mfma_f32_16x16x32_bf16 v[40:43], v[166:169], v[190:193], v[40:43]
	v_mfma_f32_16x16x32_bf16 v[36:39], v[174:177], v[190:193], v[36:39]
	v_mfma_f32_16x16x32_bf16 v[20:23], v[166:169], v[206:209], v[20:23]
	v_mfma_f32_16x16x32_bf16 v[16:19], v[174:177], v[206:209], v[16:19]
	v_mfma_f32_16x16x32_bf16 v[4:7], v[166:169], v[214:217], v[4:7]
	v_mfma_f32_16x16x32_bf16 v[0:3], v[174:177], v[214:217], v[0:3]
	s_setprio 0
	s_waitcnt vmcnt(8)
	s_barrier
	s_add_i32 s58, 0, 0x18000
	v_add_u32_e32 v146, s58, v147
	s_add_i32 s59, 0, 0x1c000
	ds_read_b128 v[140:143], v146
	ds_read_b128 v[150:153], v146 offset:1024
	ds_read_b128 v[154:157], v146 offset:2048
	ds_read_b128 v[158:161], v146 offset:3072
	v_add_u32_e32 v146, s59, v147
	ds_read_b128 v[162:165], v146
	ds_read_b128 v[166:169], v146 offset:1024
	ds_read_b128 v[170:173], v146 offset:2048
	ds_read_b128 v[174:177], v146 offset:3072
	s_add_u32 s40, s40, 0x40000
	s_addc_u32 s41, s41, 0
	s_mov_b32 m0, s46
	v_lshl_add_u64 v[222:223], s[40:41], 0, v[134:135]
	ds_read_b128 v[178:181], v149 offset:32768
	ds_read_b128 v[182:185], v149 offset:33792
	ds_read_b128 v[186:189], v149 offset:34816
	ds_read_b128 v[190:193], v149 offset:35840
	ds_read_b128 v[202:205], v149 offset:36864
	ds_read_b128 v[206:209], v149 offset:37888
	ds_read_b128 v[210:213], v149 offset:38912
	ds_read_b128 v[214:217], v149 offset:39936
	global_load_lds_dwordx4 v[222:223], off
	v_lshl_add_u64 v[222:223], s[40:41], 0, v[132:133]
	s_mov_b32 m0, s47
	s_nop 0
	global_load_lds_dwordx4 v[222:223], off
	s_cmp_lg_u64 s[12:13], 0
	s_cbranch_scc1 .Lkw_623_3
	s_waitcnt vmcnt(8)
; #define PG8_STAGE(bufoff, gbase, voff) do { _Pragma("unroll") for (int _i = 0; _i < 2; ++_i) \
;         __builtin_amdgcn_global_load_lds((const unsigned*)((const char*)(gbase) + (voff)[_i]), (PG8_LAS unsigned*)(lds + (bufoff) + ldsw + _i * 8192), 16, 0, 0); } while (0)
; #define PG8_LDA(dst, b, h) do { _Pragma("unroll") for (int m = 0; m < 4; ++m) _Pragma("unroll") for (int k = 0; k < 2; ++k) dst[m][k] = *(const PG8_LAS bf16x8*)(lds + PG8_SA(b, h) + aoff + m * 2048 + k * 1024); } while (0)
; #define PG8_MMA(ai, bj, At, Bt) do { __builtin_amdgcn_s_setprio(1); _Pragma("unroll") for (int m = 0; m < 4; ++m) _Pragma("unroll") for (int n = 0; n < 2; ++n) _Pragma("unroll") for (int k = 0; k < 2; ++k) \
;         acc[ai][bj][m][n] = __builtin_amdgcn_mfma_f32_16x16x32_bf16(Bt[n][k], At[m][k], acc[ai][bj][m][n], 0, 0, 0); __builtin_amdgcn_s_setprio(0); } while (0)
; #define PG8_WAIT_V(n) asm volatile("s_waitcnt vmcnt(" #n ")" ::: "memory")
; #define PG8_WAIT_L(n) asm volatile("s_waitcnt lgkmcnt(" #n ")" ::: "memory")
; #define PG8_BAR __builtin_amdgcn_s_barrier()
; #define PG8_SCHED __builtin_amdgcn_sched_barrier(0)
; template <class Epi, class Sched, bool ALIGN_EPI = false, bool SP2 = false>
; __device__ __forceinline__ void gemm_phase(PG8_LAS unsigned char* lds, const Gemm g, const Sched& S, const Epi& E) {
;     ...
;             PG8_WAIT_V(8); PG8_WAIT_L(0); PG8_BAR; PG8_MMA(0, 0, At, B0); PG8_MMA(0, 1, At, B1); PG8_BAR; PG8_SCHED;
;             PG8_LDA(At, 1, 1); PG8_STAGE(PG8_SB(1, 0), b3, voffB); PG8_STAGE(PG8_SB(1, 1), b3 + hstep, voffB); PG8_STAGE(PG8_SA(1, 0), a3, voffA);
;             PG8_WAIT_V(8); PG8_WAIT_L(0); PG8_BAR; PG8_MMA(1, 0, At, B0); PG8_MMA(1, 1, At, B1); PG8_BAR; PG8_SCHED;
;     ...
;         if constexpr (ALIGN_EPI) { if (wr == 0) PG8_BAR; }
;         if constexpr (!Epi::AFTER_DRAIN) { E(acc, cur, wr, wc, fr, fq); S.done(cur); }
;         if (!has_next) break;
.Lkw_623_3:
	s_waitcnt lgkmcnt(0)
	v_mfma_f32_16x16x32_bf16 v[128:131], v[140:143], v[178:181], v[128:131]
	v_mfma_f32_16x16x32_bf16 v[124:127], v[154:157], v[178:181], v[124:127]
	v_mfma_f32_16x16x32_bf16 v[112:115], v[140:143], v[186:189], v[112:115]
	v_mfma_f32_16x16x32_bf16 v[108:111], v[154:157], v[186:189], v[108:111]
	s_barrier
	s_setprio 1
	v_mfma_f32_16x16x32_bf16 v[96:99], v[140:143], v[202:205], v[96:99]
	v_mfma_f32_16x16x32_bf16 v[92:95], v[154:157], v[202:205], v[92:95]
	v_mfma_f32_16x16x32_bf16 v[80:83], v[140:143], v[210:213], v[80:83]
	v_mfma_f32_16x16x32_bf16 v[76:79], v[154:157], v[210:213], v[76:79]
	v_mfma_f32_16x16x32_bf16 v[128:131], v[150:153], v[182:185], v[128:131]
	v_mfma_f32_16x16x32_bf16 v[124:127], v[158:161], v[182:185], v[124:127]
	v_mfma_f32_16x16x32_bf16 v[112:115], v[150:153], v[190:193], v[112:115]
	v_mfma_f32_16x16x32_bf16 v[108:111], v[158:161], v[190:193], v[108:111]
	v_mfma_f32_16x16x32_bf16 v[96:99], v[150:153], v[206:209], v[96:99]
	v_mfma_f32_16x16x32_bf16 v[92:95], v[158:161], v[206:209], v[92:95]
	v_mfma_f32_16x16x32_bf16 v[80:83], v[150:153], v[214:217], v[80:83]
	v_mfma_f32_16x16x32_bf16 v[76:79], v[158:161], v[214:217], v[76:79]
	s_setprio 0
	s_setprio 1
	v_mfma_f32_16x16x32_bf16 v[120:123], v[162:165], v[178:181], v[120:123]
	v_mfma_f32_16x16x32_bf16 v[116:119], v[170:173], v[178:181], v[116:119]
	v_mfma_f32_16x16x32_bf16 v[104:107], v[162:165], v[186:189], v[104:107]
	v_mfma_f32_16x16x32_bf16 v[100:103], v[170:173], v[186:189], v[100:103]
	v_mfma_f32_16x16x32_bf16 v[88:91], v[162:165], v[202:205], v[88:91]
	v_mfma_f32_16x16x32_bf16 v[84:87], v[170:173], v[202:205], v[84:87]
	v_mfma_f32_16x16x32_bf16 v[72:75], v[162:165], v[210:213], v[72:75]
	v_mfma_f32_16x16x32_bf16 v[68:71], v[170:173], v[210:213], v[68:71]
	v_mfma_f32_16x16x32_bf16 v[120:123], v[166:169], v[182:185], v[120:123]
	v_mfma_f32_16x16x32_bf16 v[116:119], v[174:177], v[182:185], v[116:119]
	v_mfma_f32_16x16x32_bf16 v[104:107], v[166:169], v[190:193], v[104:107]
	v_mfma_f32_16x16x32_bf16 v[100:103], v[174:177], v[190:193], v[100:103]
	v_mfma_f32_16x16x32_bf16 v[88:91], v[166:169], v[206:209], v[88:91]
	v_mfma_f32_16x16x32_bf16 v[84:87], v[174:177], v[206:209], v[84:87]
	v_mfma_f32_16x16x32_bf16 v[72:75], v[166:169], v[214:217], v[72:75]
	v_mfma_f32_16x16x32_bf16 v[68:71], v[174:177], v[214:217], v[68:71]
	s_setprio 0
	s_waitcnt vmcnt(8)
	s_barrier
	s_add_i32 s40, s58, s43
	v_lshl_add_u64 v[144:145], v[144:145], 0, s[36:37]
	s_mov_b32 m0, s40
	ds_read_b128 v[178:181], v149 offset:49152
	ds_read_b128 v[182:185], v149 offset:50176
	ds_read_b128 v[186:189], v149 offset:51200
	ds_read_b128 v[190:193], v149 offset:52224
	ds_read_b128 v[202:205], v149 offset:53248
	ds_read_b128 v[206:209], v149 offset:54272
	ds_read_b128 v[210:213], v149 offset:55296
	ds_read_b128 v[214:217], v149 offset:56320
	global_load_lds_dwordx4 v[144:145], off
	s_add_i32 m0, s40, 0x2000
	s_add_u32 s22, s22, 0x40080
	v_lshl_add_u64 v[144:145], v[194:195], 0, s[36:37]
	s_addc_u32 s23, s23, 0
	s_add_i32 s40, s59, s43
	global_load_lds_dwordx4 v[144:145], off
	v_lshl_add_u64 v[144:145], s[22:23], 0, v[196:197]
	s_mov_b32 m0, s40
	s_nop 0
	global_load_lds_dwordx4 v[144:145], off
	v_lshl_add_u64 v[144:145], s[22:23], 0, v[32:33]
	s_add_i32 m0, s40, 0x2000
	s_nop 0
	global_load_lds_dwordx4 v[144:145], off
	v_lshl_add_u64 v[144:145], v[218:219], 0, s[36:37]
	s_mov_b32 m0, s49
	s_nop 0
	global_load_lds_dwordx4 v[144:145], off
	v_lshl_add_u64 v[144:145], v[220:221], 0, s[36:37]
	s_mov_b32 m0, s50
	s_nop 0
	global_load_lds_dwordx4 v[144:145], off
	s_cmp_lg_u64 s[12:13], 0
	s_cbranch_scc1 .Lkw_623_4
	s_waitcnt vmcnt(8)
.Lkw_623_4:
	s_waitcnt lgkmcnt(0)
	v_mfma_f32_16x16x32_bf16 v[64:67], v[140:143], v[178:181], v[64:67]
	v_mfma_f32_16x16x32_bf16 v[60:63], v[154:157], v[178:181], v[60:63]
	v_mfma_f32_16x16x32_bf16 v[48:51], v[140:143], v[186:189], v[48:51]
	v_mfma_f32_16x16x32_bf16 v[44:47], v[154:157], v[186:189], v[44:47]
	s_barrier
	s_setprio 1
	v_mfma_f32_16x16x32_bf16 v[28:31], v[140:143], v[202:205], v[28:31]
	v_mfma_f32_16x16x32_bf16 v[24:27], v[154:157], v[202:205], v[24:27]
	v_mfma_f32_16x16x32_bf16 v[12:15], v[140:143], v[210:213], v[12:15]
	v_mfma_f32_16x16x32_bf16 v[8:11], v[154:157], v[210:213], v[8:11]
	v_mfma_f32_16x16x32_bf16 v[64:67], v[150:153], v[182:185], v[64:67]
	v_mfma_f32_16x16x32_bf16 v[60:63], v[158:161], v[182:185], v[60:63]
	v_mfma_f32_16x16x32_bf16 v[48:51], v[150:153], v[190:193], v[48:51]
	v_mfma_f32_16x16x32_bf16 v[44:47], v[158:161], v[190:193], v[44:47]
	v_mfma_f32_16x16x32_bf16 v[28:31], v[150:153], v[206:209], v[28:31]
	v_mfma_f32_16x16x32_bf16 v[24:27], v[158:161], v[206:209], v[24:27]
	v_mfma_f32_16x16x32_bf16 v[12:15], v[150:153], v[214:217], v[12:15]
	v_mfma_f32_16x16x32_bf16 v[8:11], v[158:161], v[214:217], v[8:11]
	s_setprio 0
	s_setprio 1
	v_mfma_f32_16x16x32_bf16 v[56:59], v[162:165], v[178:181], v[56:59]
	v_mfma_f32_16x16x32_bf16 v[52:55], v[170:173], v[178:181], v[52:55]
	v_mfma_f32_16x16x32_bf16 v[40:43], v[162:165], v[186:189], v[40:43]
	v_mfma_f32_16x16x32_bf16 v[36:39], v[170:173], v[186:189], v[36:39]
	v_mfma_f32_16x16x32_bf16 v[20:23], v[162:165], v[202:205], v[20:23]
	v_mfma_f32_16x16x32_bf16 v[16:19], v[170:173], v[202:205], v[16:19]
	v_mfma_f32_16x16x32_bf16 v[4:7], v[162:165], v[210:213], v[4:7]
	v_mfma_f32_16x16x32_bf16 v[0:3], v[170:173], v[210:213], v[0:3]
	v_mfma_f32_16x16x32_bf16 v[56:59], v[166:169], v[182:185], v[56:59]
	v_mfma_f32_16x16x32_bf16 v[52:55], v[174:177], v[182:185], v[52:55]
	v_mfma_f32_16x16x32_bf16 v[40:43], v[166:169], v[190:193], v[40:43]
	v_mfma_f32_16x16x32_bf16 v[36:39], v[174:177], v[190:193], v[36:39]
	v_mfma_f32_16x16x32_bf16 v[20:23], v[166:169], v[206:209], v[20:23]
	v_mfma_f32_16x16x32_bf16 v[16:19], v[174:177], v[206:209], v[16:19]
	v_mfma_f32_16x16x32_bf16 v[4:7], v[166:169], v[214:217], v[4:7]
	v_mfma_f32_16x16x32_bf16 v[0:3], v[174:177], v[214:217], v[0:3]
	s_setprio 0
	s_waitcnt vmcnt(8)
	s_barrier
	s_add_i32 s57, s57, 2
	s_add_u32 s0, s0, 0x100
	s_addc_u32 s1, s1, 0
	s_add_u32 s55, s55, 0x100
	s_addc_u32 s56, s56, 0
	s_cmp_gt_u32 s57, 13
	s_cbranch_scc0 .LBB0_623
	s_and_b64 vcc, exec, s[12:13]
	s_cbranch_vccz .LBB0_626
	s_barrier
